# prompt attention softmax: (s-m)*log2e fused into one v_fmamk_f32 per element (169 sub+mul pairs)
# speedup vs baseline: 1.0088x; 1.0030x over previous
; #define LAS __attribute__((address_space(3)))
; __device__ __forceinline__ void phase_attn(Frame& F, const Params& p, int j) {
;     ...
;             const int qt0 = q_lo + 16 * mt, q = qt0 + fr;
;             const int qrow = prow(b, q);
;             const bf16x8 qf0 = qfa[mt][0], qf1 = qfa[mt][1];
;             const int ktb = (qt0 >> 4) - 8;
;             f32x4 s[9];
; #pragma unroll
;             for (int t = 0; t < 9; ++t) {
;                 const int kt = ktb + t > 0 ? ktb + t : 0;
;                 const LAS unsigned char* kp = F.lds + (kt * 16 - k_lo + fr) * KSTR + fq * 16;
;                 const bf16x8 kf0 = *(const LAS bf16x8*)kp, kf1 = *(const LAS bf16x8*)(kp + 64);
;                 s[t] = (f32x4){0.f, 0.f, 0.f, 0.f};
;                 s[t] = __builtin_amdgcn_mfma_f32_16x16x32_bf16(kf0, qf0, s[t], 0, 0, 0);
;                 s[t] = __builtin_amdgcn_mfma_f32_16x16x32_bf16(kf1, qf1, s[t], 0, 0, 0);
;             }
;             float m = sink;
; #pragma unroll
;             for (int t = 0; t < 9; ++t)
; #pragma unroll
;                 for (int jj = 0; jj < 4; ++jj) { const int key = (ktb + t) * 16 + fq * 4 + jj, dd = q - key; const bool ok = key >= 0 && dd >= 0 && dd < 128;
;                     s[t][jj] = ok ? s[t][jj] : -1e30f; m = fmaxf(m, s[t][jj]); }
.LBB0_1302:
	s_or_b64 exec, exec, s[14:15]
	s_lshr_b32 s16, s30, 4
	s_add_i32 s17, s16, -8
	s_max_i32 s66, s17, 0
	s_lshl_b32 s14, s66, 4
	s_sub_i32 s14, s14, s27
	v_or_b32_e32 v54, s14, v126
	v_mad_u64_u32 v[58:59], s[14:15], v54, s80, v[48:49]
	s_waitcnt lgkmcnt(0)
	s_barrier
	ds_read_b128 v[54:57], v58
	ds_read_b128 v[58:61], v58 offset:64
	s_lshl_b32 s34, s18, 6
	s_waitcnt vmcnt(9) lgkmcnt(1)
	v_mfma_f32_16x16x32_bf16 v[54:57], v[54:57], v[38:41], 0
	s_add_i32 s18, s16, -7
	s_max_i32 s65, s18, 0
	s_lshl_b32 s14, s65, 4
	s_sub_i32 s14, s14, s27
	s_waitcnt vmcnt(8) lgkmcnt(0)
	v_mfma_f32_16x16x32_bf16 v[54:57], v[58:61], v[34:37], v[54:57]
	v_or_b32_e32 v58, s14, v126
	v_mad_u64_u32 v[62:63], s[14:15], v58, s80, v[48:49]
	ds_read_b128 v[58:61], v62
	ds_read_b128 v[62:65], v62 offset:64
	s_waitcnt lgkmcnt(1)
	v_mfma_f32_16x16x32_bf16 v[58:61], v[58:61], v[38:41], 0
	s_add_i32 s19, s16, -6
	s_max_i32 s64, s19, 0
	s_lshl_b32 s14, s64, 4
	s_sub_i32 s14, s14, s27
	s_waitcnt lgkmcnt(0)
	v_mfma_f32_16x16x32_bf16 v[58:61], v[62:65], v[34:37], v[58:61]
	v_or_b32_e32 v62, s14, v126
	v_mad_u64_u32 v[76:77], s[14:15], v62, s80, v[48:49]
	ds_read_b128 v[62:65], v76
	ds_read_b128 v[76:79], v76 offset:64
	s_waitcnt lgkmcnt(1)
	v_mfma_f32_16x16x32_bf16 v[62:65], v[62:65], v[38:41], 0
	s_add_i32 s20, s16, -5
	s_max_i32 s59, s20, 0
	s_lshl_b32 s14, s59, 4
	s_sub_i32 s14, s14, s27
	s_waitcnt lgkmcnt(0)
	v_mfma_f32_16x16x32_bf16 v[62:65], v[76:79], v[34:37], v[62:65]
	v_or_b32_e32 v76, s14, v126
	v_mad_u64_u32 v[80:81], s[14:15], v76, s80, v[48:49]
	ds_read_b128 v[76:79], v80
	ds_read_b128 v[80:83], v80 offset:64
	s_waitcnt lgkmcnt(1)
	v_mfma_f32_16x16x32_bf16 v[76:79], v[76:79], v[38:41], 0
	s_add_i32 s21, s16, -4
	s_max_i32 s39, s21, 0
	s_lshl_b32 s14, s39, 4
	s_sub_i32 s14, s14, s27
	s_waitcnt lgkmcnt(0)
	v_mfma_f32_16x16x32_bf16 v[76:79], v[80:83], v[34:37], v[76:79]
	v_or_b32_e32 v80, s14, v126
	v_mad_u64_u32 v[84:85], s[14:15], v80, s80, v[48:49]
	ds_read_b128 v[80:83], v84
	ds_read_b128 v[84:87], v84 offset:64
	s_waitcnt lgkmcnt(1)
	v_mfma_f32_16x16x32_bf16 v[80:83], v[80:83], v[38:41], 0
	s_add_i32 s49, s16, -3
	s_max_i32 s38, s49, 0
	s_lshl_b32 s14, s38, 4
	s_sub_i32 s14, s14, s27
	s_waitcnt lgkmcnt(0)
	v_mfma_f32_16x16x32_bf16 v[80:83], v[84:87], v[34:37], v[80:83]
	v_or_b32_e32 v84, s14, v126
	v_mad_u64_u32 v[88:89], s[14:15], v84, s80, v[48:49]
	ds_read_b128 v[84:87], v88
	ds_read_b128 v[88:91], v88 offset:64
	s_waitcnt lgkmcnt(1)
	v_mfma_f32_16x16x32_bf16 v[84:87], v[84:87], v[38:41], 0
	s_add_i32 s67, s16, -2
	s_max_i32 s37, s67, 0
	s_lshl_b32 s14, s37, 4
	s_sub_i32 s14, s14, s27
	s_waitcnt lgkmcnt(0)
	v_mfma_f32_16x16x32_bf16 v[84:87], v[88:91], v[34:37], v[84:87]
	v_or_b32_e32 v88, s14, v126
	v_mad_u64_u32 v[92:93], s[14:15], v88, s80, v[48:49]
	ds_read_b128 v[88:91], v92
	ds_read_b128 v[92:95], v92 offset:64
	s_waitcnt lgkmcnt(1)
	v_mfma_f32_16x16x32_bf16 v[88:91], v[88:91], v[38:41], 0
	s_add_i32 s68, s16, -1
	s_max_i32 s36, s68, 0
	s_lshl_b32 s14, s36, 4
	s_sub_i32 s14, s14, s27
	s_waitcnt lgkmcnt(0)
	v_mfma_f32_16x16x32_bf16 v[88:91], v[92:95], v[34:37], v[88:91]
	v_or_b32_e32 v92, s14, v126
	v_mad_u64_u32 v[96:97], s[14:15], v92, s80, v[48:49]
	ds_read_b128 v[92:95], v96
	ds_read_b128 v[96:99], v96 offset:64
	s_waitcnt lgkmcnt(1)
	v_mfma_f32_16x16x32_bf16 v[92:95], v[92:95], v[38:41], 0
	s_sub_i32 s35, s30, s27
	s_add_i32 s25, s25, -16
	s_lshl_b32 s26, s27, 1
	s_waitcnt lgkmcnt(0)
	v_mfma_f32_16x16x32_bf16 v[92:95], v[96:99], v[34:37], v[92:95]
	v_or_b32_e32 v96, s35, v126
	v_mad_i32_i24 v100, v96, s80, v48
	ds_read_b128 v[96:99], v100
	ds_read_b128 v[100:103], v100 offset:64
	s_waitcnt lgkmcnt(1)
	v_mfma_f32_16x16x32_bf16 v[38:41], v[96:99], v[38:41], 0
	v_or_b32_e32 v104, s30, v126
	s_cmpk_gt_u32 s30, 0x70
	s_cselect_b64 s[14:15], -1, 0
	s_waitcnt lgkmcnt(0)
	v_mfma_f32_16x16x32_bf16 v[34:37], v[100:103], v[34:37], v[38:41]
	v_add_u32_e32 v75, s25, v104
	v_lshlrev_b32_e32 v168, 1, v46
	s_nop 0
	v_lshl_or_b32 v38, s17, 4, v46
	v_sub_u32_e32 v39, v104, v38
	v_cmp_gt_u32_e32 vcc, s91, v39
	s_and_b64 vcc, s[14:15], vcc
	v_sub_u32_e32 v40, v38, v104
	v_cndmask_b32_e32 v39, v219, v54, vcc
	v_cmp_lt_u32_e32 vcc, s42, v40
	s_and_b64 vcc, s[14:15], vcc
	v_add_u32_e32 v54, -2, v104
	v_cndmask_b32_e32 v40, v219, v55, vcc
	v_sub_u32_e32 v55, v54, v38
	v_cmp_gt_u32_e32 vcc, s91, v55
	s_and_b64 vcc, s[14:15], vcc
	v_max3_f32 v41, v73, v39, v40
	v_cndmask_b32_e32 v55, v219, v56, vcc
	v_add_u32_e32 v56, -3, v104
	v_sub_u32_e32 v38, v56, v38
	v_cmp_gt_u32_e32 vcc, s91, v38
	s_and_b64 vcc, s[14:15], vcc
	s_cmpk_gt_u32 s30, 0x60
	v_cndmask_b32_e32 v38, v219, v57, vcc
	v_lshl_or_b32 v57, s18, 4, v46
	v_sub_u32_e32 v96, v104, v57
	s_cselect_b64 s[14:15], -1, 0
	v_cmp_gt_u32_e32 vcc, s91, v96
	s_and_b64 vcc, s[14:15], vcc
	v_sub_u32_e32 v96, v57, v104
	v_cndmask_b32_e32 v58, v219, v58, vcc
	v_cmp_lt_u32_e32 vcc, s42, v96
	s_and_b64 vcc, s[14:15], vcc
	v_sub_u32_e32 v96, v54, v57
	v_cndmask_b32_e32 v59, v219, v59, vcc
	v_cmp_gt_u32_e32 vcc, s91, v96
	s_and_b64 vcc, s[14:15], vcc
	v_sub_u32_e32 v57, v56, v57
	v_cndmask_b32_e32 v60, v219, v60, vcc
	v_cmp_gt_u32_e32 vcc, s91, v57
	s_and_b64 vcc, s[14:15], vcc
	s_cmpk_gt_u32 s30, 0x50
	v_cndmask_b32_e32 v57, v219, v61, vcc
	v_lshl_or_b32 v61, s19, 4, v46
	v_sub_u32_e32 v96, v104, v61
	s_cselect_b64 s[14:15], -1, 0
	v_cmp_gt_u32_e32 vcc, s91, v96
	s_and_b64 vcc, s[14:15], vcc
	v_max3_f32 v41, v41, v55, v38
	v_cndmask_b32_e32 v96, v219, v62, vcc
	v_sub_u32_e32 v62, v61, v104
	v_cmp_lt_u32_e32 vcc, s42, v62
	s_and_b64 vcc, s[14:15], vcc
	v_sub_u32_e32 v62, v54, v61
	v_cndmask_b32_e32 v97, v219, v63, vcc
; #define LAS __attribute__((address_space(3)))
; __device__ __forceinline__ void phase_attn(Frame& F, const Params& p, int j) {
;     ...
;             for (int t = 0; t < 9; ++t)
; #pragma unroll
;                 for (int jj = 0; jj < 4; ++jj) { const int key = (ktb + t) * 16 + fq * 4 + jj, dd = q - key; const bool ok = key >= 0 && dd >= 0 && dd < 128;
;                     s[t][jj] = ok ? s[t][jj] : -1e30f; m = fmaxf(m, s[t][jj]); }
;             m = fmaxf(m, __shfl_xor(m, 16)); m = fmaxf(m, __shfl_xor(m, 32));
;     ...
;             for (int t = 0; t < 9; ++t) {
;                 const int kt = ktb + t > 0 ? ktb + t : 0;
; #pragma unroll
;                 for (int dt = 0; dt < 4; ++dt) {
;                     const s16x4 vf = *(const LAS s16x4*)(F.lds + VOFF + (dt * 16 + fr) * VSTR + (kt * 16 - k_lo + fq * 4) * 2);
	v_cmp_gt_u32_e32 vcc, s91, v62
	s_and_b64 vcc, s[14:15], vcc
	v_sub_u32_e32 v61, v56, v61
	v_cndmask_b32_e32 v64, v219, v64, vcc
	v_cmp_gt_u32_e32 vcc, s91, v61
	s_and_b64 vcc, s[14:15], vcc
	v_lshl_or_b32 v61, s20, 4, v46
	s_cmp_gt_u32 s30, 64
	v_sub_u32_e32 v62, v104, v61
	v_cndmask_b32_e32 v65, v219, v65, vcc
	s_cselect_b64 s[14:15], -1, 0
	v_cmp_gt_u32_e32 vcc, s91, v62
	s_and_b64 vcc, s[14:15], vcc
	v_sub_u32_e32 v62, v61, v104
	v_cndmask_b32_e32 v76, v219, v76, vcc
	v_cmp_lt_u32_e32 vcc, s42, v62
	s_and_b64 vcc, s[14:15], vcc
	v_sub_u32_e32 v62, v54, v61
	v_cndmask_b32_e32 v77, v219, v77, vcc
	v_cmp_gt_u32_e32 vcc, s91, v62
	s_and_b64 vcc, s[14:15], vcc
	v_sub_u32_e32 v61, v56, v61
	v_cndmask_b32_e32 v78, v219, v78, vcc
	v_cmp_gt_u32_e32 vcc, s91, v61
	s_and_b64 vcc, s[14:15], vcc
	v_lshl_or_b32 v61, s21, 4, v46
	s_cmp_gt_u32 s30, 48
	v_sub_u32_e32 v62, v104, v61
	v_cndmask_b32_e32 v79, v219, v79, vcc
	s_cselect_b64 s[16:17], -1, 0
	v_cmp_gt_u32_e32 vcc, s91, v62
	s_and_b64 vcc, s[16:17], vcc
	v_sub_u32_e32 v62, v61, v104
	v_cndmask_b32_e32 v80, v219, v80, vcc
	v_cmp_lt_u32_e32 vcc, s42, v62
	s_and_b64 vcc, s[16:17], vcc
	v_sub_u32_e32 v62, v54, v61
	v_cndmask_b32_e32 v81, v219, v81, vcc
	v_cmp_gt_u32_e32 vcc, s91, v62
	s_and_b64 vcc, s[16:17], vcc
	v_sub_u32_e32 v61, v56, v61
	v_cndmask_b32_e32 v82, v219, v82, vcc
	v_cmp_gt_u32_e32 vcc, s91, v61
	s_and_b64 vcc, s[16:17], vcc
	v_lshl_or_b32 v61, s49, 4, v46
	s_cmp_gt_u32 s30, 32
	v_sub_u32_e32 v62, v104, v61
	v_cndmask_b32_e32 v83, v219, v83, vcc
	s_cselect_b64 s[18:19], -1, 0
	v_cmp_gt_u32_e32 vcc, s91, v62
	s_and_b64 vcc, s[18:19], vcc
	v_sub_u32_e32 v62, v61, v104
	v_cndmask_b32_e32 v84, v219, v84, vcc
	v_cmp_lt_u32_e32 vcc, s42, v62
	s_and_b64 vcc, s[18:19], vcc
	v_sub_u32_e32 v62, v54, v61
	v_cndmask_b32_e32 v85, v219, v85, vcc
	v_cmp_gt_u32_e32 vcc, s91, v62
	s_and_b64 vcc, s[18:19], vcc
	v_sub_u32_e32 v61, v56, v61
	v_cndmask_b32_e32 v86, v219, v86, vcc
	v_cmp_gt_u32_e32 vcc, s91, v61
	s_and_b64 vcc, s[18:19], vcc
	v_lshl_or_b32 v61, s67, 4, v46
	s_cmp_gt_u32 s30, 16
	v_sub_u32_e32 v62, v104, v61
	v_cndmask_b32_e32 v87, v219, v87, vcc
	s_cselect_b64 s[20:21], -1, 0
	v_cmp_gt_u32_e32 vcc, s91, v62
	s_and_b64 vcc, s[20:21], vcc
	v_sub_u32_e32 v62, v61, v104
	v_cndmask_b32_e32 v88, v219, v88, vcc
	v_cmp_lt_u32_e32 vcc, s42, v62
	s_and_b64 vcc, s[20:21], vcc
	v_sub_u32_e32 v62, v54, v61
	v_max3_f32 v41, v41, v58, v59
	v_cndmask_b32_e32 v89, v219, v89, vcc
	v_cmp_gt_u32_e32 vcc, s91, v62
	v_max3_f32 v41, v41, v60, v57
	s_and_b64 vcc, s[20:21], vcc
	v_sub_u32_e32 v61, v56, v61
	v_max3_f32 v41, v41, v96, v97
	v_cndmask_b32_e32 v90, v219, v90, vcc
	v_cmp_gt_u32_e32 vcc, s91, v61
	v_lshl_or_b32 v61, s68, 4, v46
	v_max3_f32 v41, v41, v64, v65
	s_and_b64 vcc, s[20:21], vcc
	v_sub_u32_e32 v62, v104, v61
	v_max3_f32 v41, v41, v76, v77
	v_cndmask_b32_e32 v91, v219, v91, vcc
	v_cmp_gt_u32_e32 vcc, s91, v62
	v_max3_f32 v41, v41, v78, v79
	s_and_b64 vcc, s[10:11], vcc
	v_sub_u32_e32 v62, v61, v104
	v_max3_f32 v41, v41, v80, v81
	v_cndmask_b32_e32 v92, v219, v92, vcc
	v_cmp_lt_u32_e32 vcc, s42, v62
	v_max3_f32 v41, v41, v82, v83
	s_and_b64 vcc, s[10:11], vcc
	v_sub_u32_e32 v54, v54, v61
	v_max3_f32 v41, v41, v84, v85
	v_cndmask_b32_e32 v93, v219, v93, vcc
	v_cmp_gt_u32_e32 vcc, s91, v54
	v_max3_f32 v41, v41, v86, v87
	s_and_b64 vcc, s[10:11], vcc
	v_sub_u32_e32 v54, v56, v61
	v_max3_f32 v41, v41, v88, v89
	v_cndmask_b32_e32 v94, v219, v94, vcc
	v_cmp_gt_u32_e32 vcc, s91, v54
	v_max3_f32 v41, v41, v90, v91
	s_and_b64 vcc, s[10:11], vcc
	v_max3_f32 v41, v41, v92, v93
	v_cndmask_b32_e32 v95, v219, v95, vcc
	v_max3_f32 v41, v41, v94, v95
	v_cndmask_b32_e64 v34, v219, v34, s[2:3]
	v_cndmask_b32_e64 v35, v219, v35, s[4:5]
	v_max3_f32 v41, v41, v34, v35
	v_cndmask_b32_e64 v36, v219, v36, s[6:7]
	v_cndmask_b32_e64 v37, v219, v37, s[8:9]
	v_max3_f32 v41, v41, v36, v37
	ds_bpermute_b32 v54, v67, v41
	s_lshl_b32 s49, s66, 5
	s_sub_i32 s49, s49, s26
	s_lshl_b32 s39, s39, 5
	s_sub_i32 s39, s39, s26
	s_waitcnt lgkmcnt(0)
	v_max_f32_e32 v54, v54, v54
	v_max_f32_e32 v41, v41, v54
	ds_bpermute_b32 v54, v68, v41
	s_lshl_b32 s38, s38, 5
	s_sub_i32 s38, s38, s26
	s_lshl_b32 s37, s37, 5
	s_sub_i32 s37, s37, s26
	s_waitcnt lgkmcnt(0)
; #define LAS __attribute__((address_space(3)))
; __device__ __forceinline__ unsigned cvt_pk_bf16(float lo, float hi) { unsigned r; asm volatile("v_cvt_pk_bf16_f32 %0, %1, %2" : "=v"(r) : "v"(lo), "v"(hi)); return r; }
; __device__ __forceinline__ void phase_attn(Frame& F, const Params& p, int j) {
;     ...
;             float m = sink;
; #pragma unroll
;             for (int t = 0; t < 9; ++t)
; #pragma unroll
;                 for (int jj = 0; jj < 4; ++jj) { const int key = (ktb + t) * 16 + fq * 4 + jj, dd = q - key; const bool ok = key >= 0 && dd >= 0 && dd < 128;
;                     s[t][jj] = ok ? s[t][jj] : -1e30f; m = fmaxf(m, s[t][jj]); }
;             m = fmaxf(m, __shfl_xor(m, 16)); m = fmaxf(m, __shfl_xor(m, 32));
;             float l = 0.f; s16x4 pf[9];
; #pragma unroll
;             for (int t = 0; t < 9; ++t) {
;                 float pe[4];
; #pragma unroll
;                 for (int jj = 0; jj < 4; ++jj) { pe[jj] = __expf(s[t][jj] - m); l += pe[jj]; }
;                 u32x2 w; w.x = cvt_pk_bf16(pe[0], pe[1]); w.y = cvt_pk_bf16(pe[2], pe[3]);
;                 pf[t] = __builtin_bit_cast(s16x4, w);
;             }
;             l += __shfl_xor(l, 16); l += __shfl_xor(l, 32);
;             const float rden = 1.0f / (l + __expf(sink - m));
;             f32x4 o[4];
; #pragma unroll
;             for (int dt = 0; dt < 4; ++dt) o[dt] = (f32x4){0.f, 0.f, 0.f, 0.f};
; #pragma unroll
;             for (int t = 0; t < 9; ++t) {
;                 const int kt = ktb + t > 0 ? ktb + t : 0;
; #pragma unroll
;                 for (int dt = 0; dt < 4; ++dt) {
;                     const s16x4 vf = *(const LAS s16x4*)(F.lds + VOFF + (dt * 16 + fr) * VSTR + (kt * 16 - k_lo + fq * 4) * 2);
;                     o[dt] = __builtin_amdgcn_mfma_f32_16x16x16bf16_1k(vf, pf[t], o[dt], 0, 0, 0);
;                 }
;             }
	v_max_f32_e32 v54, v54, v54
	v_max_f32_e32 v98, v41, v54
	v_mul_f32_e32 v136, 0xbfb8aa3b, v98
	v_fmamk_f32 v39, v39, 0x3fb8aa3b, v136
	v_exp_f32_e32 v39, v39
	v_fmamk_f32 v40, v40, 0x3fb8aa3b, v136
	v_exp_f32_e32 v40, v40
	v_fmamk_f32 v54, v55, 0x3fb8aa3b, v136
	v_exp_f32_e32 v54, v54
	v_fmamk_f32 v38, v38, 0x3fb8aa3b, v136
	v_exp_f32_e32 v38, v38
	v_add_f32_e32 v41, 0, v39
	v_add_f32_e32 v41, v40, v41
	v_add_f32_e32 v41, v54, v41
	v_add_f32_e32 v41, v38, v41
	v_cvt_pk_bf16_f32 v62, v39, v40
	v_cvt_pk_bf16_f32 v63, v54, v38
	v_fmamk_f32 v38, v58, 0x3fb8aa3b, v136
	v_exp_f32_e32 v38, v38
	v_fmamk_f32 v40, v59, 0x3fb8aa3b, v136
	v_exp_f32_e32 v40, v40
	v_add_f32_e32 v39, v38, v41
	v_fmamk_f32 v41, v60, 0x3fb8aa3b, v136
	v_exp_f32_e32 v41, v41
	v_fmamk_f32 v54, v57, 0x3fb8aa3b, v136
	v_exp_f32_e32 v54, v54
	v_cvt_pk_bf16_f32 v60, v38, v40
	v_add_f32_e32 v39, v40, v39
	v_fmamk_f32 v38, v96, 0x3fb8aa3b, v136
	v_add_f32_e32 v39, v41, v39
	v_cvt_pk_bf16_f32 v61, v41, v54
	v_exp_f32_e32 v38, v38
	v_fmamk_f32 v40, v97, 0x3fb8aa3b, v136
	v_add_f32_e32 v39, v54, v39
	v_exp_f32_e32 v40, v40
	v_fmamk_f32 v41, v64, 0x3fb8aa3b, v136
	v_exp_f32_e32 v41, v41
	v_fmamk_f32 v54, v65, 0x3fb8aa3b, v136
	v_exp_f32_e32 v54, v54
	v_add_f32_e32 v39, v38, v39
	v_cvt_pk_bf16_f32 v64, v38, v40
	v_add_f32_e32 v39, v40, v39
	v_fmamk_f32 v38, v76, 0x3fb8aa3b, v136
	v_add_f32_e32 v39, v41, v39
	v_cvt_pk_bf16_f32 v65, v41, v54
	v_exp_f32_e32 v38, v38
	v_fmamk_f32 v40, v77, 0x3fb8aa3b, v136
	v_add_f32_e32 v39, v54, v39
	v_exp_f32_e32 v40, v40
	v_fmamk_f32 v41, v78, 0x3fb8aa3b, v136
	v_exp_f32_e32 v41, v41
	v_fmamk_f32 v54, v79, 0x3fb8aa3b, v136
	v_exp_f32_e32 v54, v54
	v_add_f32_e32 v39, v38, v39
	v_cvt_pk_bf16_f32 v58, v38, v40
	v_add_f32_e32 v39, v40, v39
	v_fmamk_f32 v38, v80, 0x3fb8aa3b, v136
	v_add_f32_e32 v39, v41, v39
	v_cvt_pk_bf16_f32 v59, v41, v54
	v_exp_f32_e32 v38, v38
	v_fmamk_f32 v40, v81, 0x3fb8aa3b, v136
	v_add_f32_e32 v39, v54, v39
	v_exp_f32_e32 v40, v40
	v_fmamk_f32 v41, v82, 0x3fb8aa3b, v136
	v_exp_f32_e32 v41, v41
	v_fmamk_f32 v54, v83, 0x3fb8aa3b, v136
	v_exp_f32_e32 v54, v54
	v_add_f32_e32 v39, v38, v39
	v_cvt_pk_bf16_f32 v56, v38, v40
	v_add_f32_e32 v39, v40, v39
	v_fmamk_f32 v38, v84, 0x3fb8aa3b, v136
	v_add_f32_e32 v39, v41, v39
	v_cvt_pk_bf16_f32 v57, v41, v54
	v_exp_f32_e32 v38, v38
	v_fmamk_f32 v40, v85, 0x3fb8aa3b, v136
	v_add_f32_e32 v39, v54, v39
	v_exp_f32_e32 v40, v40
	v_fmamk_f32 v41, v86, 0x3fb8aa3b, v136
	v_exp_f32_e32 v41, v41
	v_fmamk_f32 v54, v87, 0x3fb8aa3b, v136
	v_exp_f32_e32 v55, v54
	v_add_f32_e32 v39, v38, v39
	v_add_f32_e32 v39, v40, v39
	v_cvt_pk_bf16_f32 v54, v38, v40
	v_add_f32_e32 v39, v41, v39
	v_fmamk_f32 v38, v88, 0x3fb8aa3b, v136
	v_add_f32_e32 v39, v55, v39
	v_cvt_pk_bf16_f32 v55, v41, v55
	v_exp_f32_e32 v38, v38
	v_fmamk_f32 v40, v89, 0x3fb8aa3b, v136
	v_exp_f32_e32 v40, v40
	v_fmamk_f32 v41, v90, 0x3fb8aa3b, v136
	v_exp_f32_e32 v41, v41
	v_fmamk_f32 v76, v91, 0x3fb8aa3b, v136
	v_exp_f32_e32 v76, v76
	v_add_f32_e32 v39, v38, v39
	v_add_f32_e32 v39, v40, v39
	v_add_f32_e32 v39, v41, v39
	v_cvt_pk_bf16_f32 v40, v38, v40
	v_add_f32_e32 v39, v76, v39
	v_cvt_pk_bf16_f32 v41, v41, v76
	v_fmamk_f32 v38, v92, 0x3fb8aa3b, v136
	v_exp_f32_e32 v38, v38
	v_fmamk_f32 v76, v93, 0x3fb8aa3b, v136
	v_exp_f32_e32 v76, v76
	v_fmamk_f32 v77, v94, 0x3fb8aa3b, v136
	v_exp_f32_e32 v77, v77
	v_fmamk_f32 v78, v95, 0x3fb8aa3b, v136
	v_exp_f32_e32 v78, v78
	v_add_f32_e32 v39, v38, v39
	v_fmamk_f32 v34, v34, 0x3fb8aa3b, v136
	v_add_f32_e32 v39, v76, v39
	v_exp_f32_e32 v34, v34
	v_fmamk_f32 v35, v35, 0x3fb8aa3b, v136
	v_add_f32_e32 v39, v77, v39
	v_exp_f32_e32 v35, v35
	v_fmamk_f32 v36, v36, 0x3fb8aa3b, v136
	v_add_f32_e32 v79, v78, v39
	v_cvt_pk_bf16_f32 v38, v38, v76
	v_cvt_pk_bf16_f32 v39, v77, v78
	v_exp_f32_e32 v77, v36
	v_fmamk_f32 v37, v37, 0x3fb8aa3b, v136
	v_exp_f32_e32 v37, v37
	v_add_f32_e32 v76, v34, v79
	v_add_f32_e32 v76, v35, v76
	v_add_f32_e32 v36, v77, v76
	v_add_f32_e32 v76, v37, v36
	v_cvt_pk_bf16_f32 v36, v34, v35
	ds_bpermute_b32 v34, v67, v76
	v_add_u32_e32 v86, s49, v70
	v_cvt_pk_bf16_f32 v37, v77, v37
	ds_read_b64 v[78:79], v86 offset:36352
	ds_read_b64 v[82:83], v86 offset:42752
	s_waitcnt lgkmcnt(2)
	v_add_f32_e32 v34, v76, v34
	ds_bpermute_b32 v35, v68, v34
	s_lshl_b32 s49, s65, 5
	s_sub_i32 s49, s49, s26
	v_add_u32_e32 v90, s49, v70
	s_waitcnt lgkmcnt(2)
	v_mfma_f32_16x16x16_bf16 v[78:81], v[78:79], v[62:63], 0
	s_waitcnt lgkmcnt(0)
	v_add_f32_e32 v34, v34, v35
	v_fmamk_f32 v35, v73, 0x3fb8aa3b, v136
	v_exp_f32_e32 v35, v35
	v_mfma_f32_16x16x16_bf16 v[82:85], v[82:83], v[62:63], 0
	s_lshl_b32 s49, s64, 5
	s_sub_i32 s49, s49, s26
	v_add_f32_e32 v35, v35, v34
	v_cndmask_b32_e64 v34, v74, v75, s[10:11]
	ds_read_b64 v[74:75], v86 offset:29952
	ds_read_b64 v[86:87], v86 offset:49152
	s_waitcnt lgkmcnt(1)
	v_mfma_f32_16x16x16_bf16 v[74:77], v[74:75], v[62:63], 0
	s_lshl_b32 s36, s36, 5
	s_sub_i32 s36, s36, s26
	s_lshl_b32 s82, s34, 1
	s_waitcnt lgkmcnt(0)
	v_mfma_f32_16x16x16_bf16 v[86:89], v[86:87], v[62:63], 0
	ds_read_b64 v[62:63], v90 offset:29952
	s_waitcnt lgkmcnt(0)
	v_mfma_f32_16x16x16_bf16 v[74:77], v[62:63], v[60:61], v[74:77]
	ds_read_b64 v[62:63], v90 offset:36352
	s_waitcnt lgkmcnt(0)
	v_mfma_f32_16x16x16_bf16 v[78:81], v[62:63], v[60:61], v[78:81]
	ds_read_b64 v[62:63], v90 offset:42752
	s_waitcnt lgkmcnt(0)
	v_mfma_f32_16x16x16_bf16 v[82:85], v[62:63], v[60:61], v[82:85]
	ds_read_b64 v[62:63], v90 offset:49152
	s_waitcnt lgkmcnt(0)
	v_mfma_f32_16x16x16_bf16 v[60:63], v[62:63], v[60:61], v[86:89]
	s_nop 2
	v_add_u32_e32 v88, s49, v70
	ds_read_b64 v[86:87], v88 offset:29952
	s_lshl_b32 s49, s59, 5
	s_waitcnt lgkmcnt(0)
; #define LAS __attribute__((address_space(3)))
; __device__ __forceinline__ unsigned cvt_pk_bf16(float lo, float hi) { unsigned r; asm volatile("v_cvt_pk_bf16_f32 %0, %1, %2" : "=v"(r) : "v"(lo), "v"(hi)); return r; }
; __device__ __forceinline__ void phase_attn(Frame& F, const Params& p, int j) {
;     ...
; #pragma unroll
;             for (int t = 0; t < 9; ++t) {
;                 const int kt = ktb + t > 0 ? ktb + t : 0;
;                 const LAS unsigned char* kp = F.lds + (kt * 16 - k_lo + fr) * KSTR + fq * 16;
;                 const bf16x8 kf0 = *(const LAS bf16x8*)kp, kf1 = *(const LAS bf16x8*)(kp + 64);
;     ...
; #pragma unroll
;             for (int t = 0; t < 9; ++t) {
;                 const int kt = ktb + t > 0 ? ktb + t : 0;
; #pragma unroll
;                 for (int dt = 0; dt < 4; ++dt) {
;                     const s16x4 vf = *(const LAS s16x4*)(F.lds + VOFF + (dt * 16 + fr) * VSTR + (kt * 16 - k_lo + fq * 4) * 2);
;                     o[dt] = __builtin_amdgcn_mfma_f32_16x16x16bf16_1k(vf, pf[t], o[dt], 0, 0, 0);
;                 }
;             }
;             bf16_t* op = F.OB + (size_t)qrow * D + h * 64 + fq * 4;
; #pragma unroll
;             for (int dt = 0; dt < 4; ++dt) { u32x2 w; w.x = cvt_pk_bf16(o[dt][0] * rden, o[dt][1] * rden); w.y = cvt_pk_bf16(o[dt][2] * rden, o[dt][3] * rden); *(u32x2*)(op + dt * 16) = w; }
	v_mfma_f32_16x16x16_bf16 v[74:77], v[86:87], v[64:65], v[74:77]
	ds_read_b64 v[86:87], v88 offset:36352
	s_sub_i32 s49, s49, s26
	s_waitcnt lgkmcnt(0)
	v_mfma_f32_16x16x16_bf16 v[78:81], v[86:87], v[64:65], v[78:81]
	ds_read_b64 v[86:87], v88 offset:42752
	s_waitcnt lgkmcnt(0)
	v_mfma_f32_16x16x16_bf16 v[82:85], v[86:87], v[64:65], v[82:85]
	ds_read_b64 v[86:87], v88 offset:49152
	s_waitcnt lgkmcnt(0)
	v_mfma_f32_16x16x16_bf16 v[60:63], v[86:87], v[64:65], v[60:63]
	v_add_u32_e32 v86, s49, v70
	ds_read_b64 v[64:65], v86 offset:29952
	s_lshr_b32 s49, s31, 4
	s_waitcnt lgkmcnt(0)
	v_mfma_f32_16x16x16_bf16 v[74:77], v[64:65], v[58:59], v[74:77]
	ds_read_b64 v[64:65], v86 offset:36352
	s_add_i32 s65, s49, -8
	s_max_i32 s64, s65, 0
	s_waitcnt lgkmcnt(0)
	v_mfma_f32_16x16x16_bf16 v[78:81], v[64:65], v[58:59], v[78:81]
	ds_read_b64 v[64:65], v86 offset:42752
	s_lshl_b32 s34, s64, 4
	s_sub_i32 s34, s34, s27
	s_waitcnt lgkmcnt(0)
	v_mfma_f32_16x16x16_bf16 v[82:85], v[64:65], v[58:59], v[82:85]
	ds_read_b64 v[64:65], v86 offset:49152
	v_add_u32_e32 v86, s39, v70
	s_add_i32 s68, s49, -7
	s_waitcnt lgkmcnt(0)
	v_mfma_f32_16x16x16_bf16 v[58:61], v[64:65], v[58:59], v[60:63]
	s_nop 2
	ds_read_b64 v[62:63], v86 offset:29952
	s_max_i32 s59, s68, 0
	s_add_i32 s69, s49, -6
	s_waitcnt lgkmcnt(0)
	v_mfma_f32_16x16x16_bf16 v[62:65], v[62:63], v[56:57], v[74:77]
	s_nop 2
	ds_read_b64 v[74:75], v86 offset:36352
	s_max_i32 s39, s69, 0
	s_add_i32 s88, s49, -5
	s_waitcnt lgkmcnt(0)
	v_mfma_f32_16x16x16_bf16 v[74:77], v[74:75], v[56:57], v[78:81]
	s_nop 2
	ds_read_b64 v[78:79], v86 offset:42752
	s_add_i32 s89, s49, -4
	s_add_i32 s94, s49, -3
	s_waitcnt lgkmcnt(0)
	v_mfma_f32_16x16x16_bf16 v[78:81], v[78:79], v[56:57], v[82:85]
	s_nop 2
	ds_read_b64 v[82:83], v86 offset:49152
	s_add_i32 s95, s49, -2
	s_waitcnt lgkmcnt(0)
	v_mfma_f32_16x16x16_bf16 v[56:59], v[82:83], v[56:57], v[58:61]
	v_add_u32_e32 v82, s38, v70
	s_nop 1
	ds_read_b64 v[60:61], v82 offset:29952
	s_max_i32 s38, s88, 0
	s_waitcnt lgkmcnt(0)
	v_mfma_f32_16x16x16_bf16 v[60:63], v[60:61], v[54:55], v[62:65]
	s_nop 2
	ds_read_b64 v[64:65], v82 offset:36352
	s_waitcnt lgkmcnt(0)
	v_mfma_f32_16x16x16_bf16 v[74:77], v[64:65], v[54:55], v[74:77]
	ds_read_b64 v[64:65], v82 offset:42752
	s_waitcnt lgkmcnt(0)
	v_mfma_f32_16x16x16_bf16 v[78:81], v[64:65], v[54:55], v[78:81]
	ds_read_b64 v[64:65], v82 offset:49152
	v_add_u32_e32 v82, s37, v70
	s_waitcnt lgkmcnt(0)
	v_mfma_f32_16x16x16_bf16 v[54:57], v[64:65], v[54:55], v[56:59]
	s_nop 2
	ds_read_b64 v[58:59], v82 offset:29952
	s_waitcnt lgkmcnt(0)
	v_mfma_f32_16x16x16_bf16 v[58:61], v[58:59], v[40:41], v[60:63]
	s_nop 2
	ds_read_b64 v[62:63], v82 offset:36352
	s_waitcnt lgkmcnt(0)
	v_mfma_f32_16x16x16_bf16 v[62:65], v[62:63], v[40:41], v[74:77]
	s_nop 2
	ds_read_b64 v[74:75], v82 offset:42752
	s_waitcnt lgkmcnt(0)
	v_mfma_f32_16x16x16_bf16 v[74:77], v[74:75], v[40:41], v[78:81]
	s_nop 2
	ds_read_b64 v[78:79], v82 offset:49152
	s_waitcnt lgkmcnt(0)
	v_mfma_f32_16x16x16_bf16 v[54:57], v[78:79], v[40:41], v[54:57]
	v_add_u32_e32 v78, s36, v70
	ds_read_b64 v[40:41], v78 offset:29952
	s_waitcnt lgkmcnt(0)
	v_mfma_f32_16x16x16_bf16 v[58:61], v[40:41], v[38:39], v[58:61]
	ds_read_b64 v[40:41], v78 offset:36352
	s_waitcnt lgkmcnt(0)
	v_mfma_f32_16x16x16_bf16 v[62:65], v[40:41], v[38:39], v[62:65]
	ds_read_b64 v[40:41], v78 offset:42752
	s_waitcnt lgkmcnt(0)
	v_mfma_f32_16x16x16_bf16 v[74:77], v[40:41], v[38:39], v[74:77]
	ds_read_b64 v[40:41], v78 offset:49152
	v_lshl_add_u32 v78, s35, 1, v70
	s_waitcnt lgkmcnt(0)
	v_mfma_f32_16x16x16_bf16 v[38:41], v[40:41], v[38:39], v[54:57]
	s_nop 2
	ds_read_b64 v[54:55], v78 offset:29952
	s_waitcnt lgkmcnt(0)
	v_mfma_f32_16x16x16_bf16 v[54:57], v[54:55], v[36:37], v[58:61]
	s_nop 2
	ds_read_b64 v[58:59], v78 offset:36352
	s_waitcnt lgkmcnt(0)
	v_mfma_f32_16x16x16_bf16 v[58:61], v[58:59], v[36:37], v[62:65]
	s_nop 2
	ds_read_b64 v[62:63], v78 offset:42752
	s_waitcnt lgkmcnt(0)
	v_mfma_f32_16x16x16_bf16 v[62:65], v[62:63], v[36:37], v[74:77]
	s_nop 2
	ds_read_b64 v[74:75], v78 offset:49152
	s_waitcnt lgkmcnt(0)
	v_mfma_f32_16x16x16_bf16 v[36:39], v[74:75], v[36:37], v[38:41]
	s_nop 2
	v_div_scale_f32 v40, s[36:37], v35, v35, 1.0
	v_rcp_f32_e32 v41, v40
	s_max_i32 s37, s89, 0
	s_max_i32 s36, s94, 0
	v_fma_f32 v74, -v40, v41, 1.0
	v_fmac_f32_e32 v41, v74, v41
	v_div_scale_f32 v74, vcc, 1.0, v35, 1.0
	v_mul_f32_e32 v75, v74, v41
	v_fma_f32 v76, -v40, v75, v74
	v_fmac_f32_e32 v75, v76, v41
	v_fma_f32 v40, -v40, v75, v74
	v_div_fmas_f32 v40, v40, v41, v75
	v_div_fixup_f32 v74, v40, v35, 1.0
	v_ashrrev_i32_e32 v35, 31, v34
	v_lshlrev_b64 v[34:35], 12, v[34:35]
	v_lshl_add_u64 v[34:35], s[86:87], 0, v[34:35]
	v_mul_f32_e32 v40, v74, v54
	v_mul_f32_e32 v41, v74, v55
	v_lshl_add_u64 v[34:35], v[34:35], 0, s[82:83]
	v_cvt_pk_bf16_f32 v40, v40, v41
	v_mul_f32_e32 v41, v74, v56
	v_lshl_add_u64 v[34:35], v[34:35], 0, v[168:169]
	v_mul_f32_e32 v54, v74, v57
	v_cvt_pk_bf16_f32 v41, v41, v54
	global_store_dwordx2 v[34:35], v[40:41], off
	v_mul_f32_e32 v40, v74, v58
	v_mul_f32_e32 v41, v74, v59
	v_cvt_pk_bf16_f32 v40, v40, v41
	v_mul_f32_e32 v41, v74, v60
	v_mul_f32_e32 v54, v74, v61
	v_cvt_pk_bf16_f32 v41, v41, v54
	global_store_dwordx2 v[34:35], v[40:41], off offset:32
	v_mul_f32_e32 v40, v74, v62
	v_mul_f32_e32 v41, v74, v63
	v_cvt_pk_bf16_f32 v40, v40, v41
	v_mul_f32_e32 v41, v74, v64
	v_mul_f32_e32 v36, v74, v36
	v_mul_f32_e32 v37, v74, v37
	v_mul_f32_e32 v54, v74, v65
	v_cvt_pk_bf16_f32 v41, v41, v54
	global_store_dwordx2 v[34:35], v[40:41], off offset:64
	v_cvt_pk_bf16_f32 v36, v36, v37
	v_mul_f32_e32 v37, v74, v38
	v_mul_f32_e32 v38, v74, v39
	v_cvt_pk_bf16_f32 v37, v37, v38
	global_store_dwordx2 v[34:35], v[36:37], off offset:96
	v_or_b32_e32 v36, s34, v126
	v_mad_u64_u32 v[40:41], s[34:35], v36, s80, v[48:49]
	ds_read_b128 v[36:39], v40
	ds_read_b128 v[54:57], v40 offset:64
	s_waitcnt vmcnt(11) lgkmcnt(1)
; #define LAS __attribute__((address_space(3)))
; __device__ __forceinline__ void phase_attn(Frame& F, const Params& p, int j) {
;     ...
; #pragma unroll
;             for (int t = 0; t < 9; ++t) {
;                 const int kt = ktb + t > 0 ? ktb + t : 0;
;                 const LAS unsigned char* kp = F.lds + (kt * 16 - k_lo + fr) * KSTR + fq * 16;
;                 const bf16x8 kf0 = *(const LAS bf16x8*)kp, kf1 = *(const LAS bf16x8*)(kp + 64);
;                 s[t] = (f32x4){0.f, 0.f, 0.f, 0.f};
;                 s[t] = __builtin_amdgcn_mfma_f32_16x16x32_bf16(kf0, qf0, s[t], 0, 0, 0);
;                 s[t] = __builtin_amdgcn_mfma_f32_16x16x32_bf16(kf1, qf1, s[t], 0, 0, 0);
;             }
;             float m = sink;
; #pragma unroll
;             for (int t = 0; t < 9; ++t)
; #pragma unroll
;                 for (int jj = 0; jj < 4; ++jj) { const int key = (ktb + t) * 16 + fq * 4 + jj, dd = q - key; const bool ok = key >= 0 && dd >= 0 && dd < 128;
;                     s[t][jj] = ok ? s[t][jj] : -1e30f; m = fmaxf(m, s[t][jj]); }
	v_mfma_f32_16x16x32_bf16 v[36:39], v[36:39], v[30:33], 0
	s_lshl_b32 s34, s59, 4
	s_sub_i32 s34, s34, s27
	v_or_b32_e32 v40, s34, v126
	v_mad_u64_u32 v[40:41], s[34:35], v40, s80, v[48:49]
	s_waitcnt vmcnt(10) lgkmcnt(0)
	v_mfma_f32_16x16x32_bf16 v[36:39], v[54:57], v[26:29], v[36:39]
	ds_read_b128 v[54:57], v40
	ds_read_b128 v[58:61], v40 offset:64
	s_lshl_b32 s34, s39, 4
	s_sub_i32 s34, s34, s27
	s_waitcnt lgkmcnt(1)
	v_mfma_f32_16x16x32_bf16 v[54:57], v[54:57], v[30:33], 0
	v_or_b32_e32 v40, s34, v126
	v_mad_u64_u32 v[40:41], s[34:35], v40, s80, v[48:49]
	s_waitcnt lgkmcnt(0)
	v_mfma_f32_16x16x32_bf16 v[54:57], v[58:61], v[26:29], v[54:57]
	ds_read_b128 v[58:61], v40
	ds_read_b128 v[62:65], v40 offset:64
	s_lshl_b32 s34, s38, 4
	s_sub_i32 s34, s34, s27
	s_waitcnt lgkmcnt(1)
	v_mfma_f32_16x16x32_bf16 v[58:61], v[58:61], v[30:33], 0
	v_or_b32_e32 v40, s34, v126
	v_mad_u64_u32 v[40:41], s[34:35], v40, s80, v[48:49]
	s_waitcnt lgkmcnt(0)
	v_mfma_f32_16x16x32_bf16 v[58:61], v[62:65], v[26:29], v[58:61]
	ds_read_b128 v[62:65], v40
	ds_read_b128 v[74:77], v40 offset:64
	s_lshl_b32 s34, s37, 4
	s_sub_i32 s34, s34, s27
	s_waitcnt lgkmcnt(1)
	v_mfma_f32_16x16x32_bf16 v[62:65], v[62:65], v[30:33], 0
	v_or_b32_e32 v40, s34, v126
	v_mad_u64_u32 v[40:41], s[34:35], v40, s80, v[48:49]
	s_waitcnt lgkmcnt(0)
	v_mfma_f32_16x16x32_bf16 v[62:65], v[74:77], v[26:29], v[62:65]
	ds_read_b128 v[74:77], v40
	ds_read_b128 v[78:81], v40 offset:64
	s_lshl_b32 s34, s36, 4
	s_sub_i32 s34, s34, s27
	s_waitcnt lgkmcnt(1)
	v_mfma_f32_16x16x32_bf16 v[74:77], v[74:77], v[30:33], 0
	v_or_b32_e32 v40, s34, v126
	v_mad_u64_u32 v[40:41], s[34:35], v40, s80, v[48:49]
	s_waitcnt lgkmcnt(0)
	v_mfma_f32_16x16x32_bf16 v[74:77], v[78:81], v[26:29], v[74:77]
	ds_read_b128 v[78:81], v40
	ds_read_b128 v[82:85], v40 offset:64
	s_max_i32 s35, s95, 0
	s_lshl_b32 s34, s35, 4
	s_waitcnt lgkmcnt(1)
	v_mfma_f32_16x16x32_bf16 v[78:81], v[78:81], v[30:33], 0
	s_sub_i32 s34, s34, s27
	v_or_b32_e32 v40, s34, v126
	v_mad_u64_u32 v[40:41], s[66:67], v40, s80, v[48:49]
	s_waitcnt lgkmcnt(0)
	v_mfma_f32_16x16x32_bf16 v[78:81], v[82:85], v[26:29], v[78:81]
	ds_read_b128 v[82:85], v40
	ds_read_b128 v[86:89], v40 offset:64
	s_add_i32 s34, s49, -1
	s_lshl_b32 s49, s34, 4
	s_waitcnt lgkmcnt(1)
	v_mfma_f32_16x16x32_bf16 v[82:85], v[82:85], v[30:33], 0
	s_sub_i32 s66, s49, s27
	v_or_b32_e32 v40, s66, v126
	v_mad_i32_i24 v40, v40, s80, v48
	s_waitcnt lgkmcnt(0)
	v_mfma_f32_16x16x32_bf16 v[82:85], v[86:89], v[26:29], v[82:85]
	ds_read_b128 v[86:89], v40
	ds_read_b128 v[90:93], v40 offset:64
	v_or_b32_e32 v35, s31, v126
	s_sub_i32 s31, s31, s27
	s_waitcnt lgkmcnt(1)
	v_mfma_f32_16x16x32_bf16 v[86:89], v[86:89], v[30:33], 0
	v_or_b32_e32 v40, s31, v126
	v_mad_i32_i24 v40, v40, s80, v48
	s_cmpk_gt_u32 s30, 0x6f
	s_waitcnt lgkmcnt(0)
	v_mfma_f32_16x16x32_bf16 v[86:89], v[90:93], v[26:29], v[86:89]
	ds_read_b128 v[90:93], v40
	ds_read_b128 v[94:97], v40 offset:64
	s_cselect_b64 s[66:67], -1, 0
	v_add_u32_e32 v34, s25, v35
	s_waitcnt lgkmcnt(1)
	v_mfma_f32_16x16x32_bf16 v[30:33], v[90:93], v[30:33], 0
	s_waitcnt lgkmcnt(0)
	v_mfma_f32_16x16x32_bf16 v[26:29], v[94:97], v[26:29], v[30:33]
	s_nop 5
	v_lshl_or_b32 v30, s65, 4, v46
	v_sub_u32_e32 v31, v35, v30
	v_cmp_gt_u32_e32 vcc, s91, v31
	s_and_b64 vcc, s[66:67], vcc
	v_sub_u32_e32 v32, v30, v35
	v_cndmask_b32_e32 v31, v219, v36, vcc
	v_cmp_lt_u32_e32 vcc, s42, v32
	s_and_b64 vcc, s[66:67], vcc
	v_add_u32_e32 v36, -2, v35
	v_cndmask_b32_e32 v32, v219, v37, vcc
	v_sub_u32_e32 v37, v36, v30
	v_cmp_gt_u32_e32 vcc, s91, v37
	s_and_b64 vcc, s[66:67], vcc
	v_max3_f32 v33, v73, v31, v32
	v_cndmask_b32_e32 v37, v219, v38, vcc
	v_add_u32_e32 v38, -3, v35
	v_sub_u32_e32 v30, v38, v30
	v_cmp_gt_u32_e32 vcc, s91, v30
	s_and_b64 vcc, s[66:67], vcc
	s_cmpk_gt_u32 s30, 0x5f
	v_cndmask_b32_e32 v30, v219, v39, vcc
	v_lshl_or_b32 v39, s68, 4, v46
	v_sub_u32_e32 v40, v35, v39
	s_cselect_b64 s[66:67], -1, 0
	v_cmp_gt_u32_e32 vcc, s91, v40
	s_and_b64 vcc, s[66:67], vcc
	v_sub_u32_e32 v41, v39, v35
	v_cndmask_b32_e32 v40, v219, v54, vcc
	v_cmp_lt_u32_e32 vcc, s42, v41
	s_and_b64 vcc, s[66:67], vcc
	v_sub_u32_e32 v54, v36, v39
	v_cndmask_b32_e32 v41, v219, v55, vcc
	v_cmp_gt_u32_e32 vcc, s91, v54
	s_and_b64 vcc, s[66:67], vcc
	v_sub_u32_e32 v39, v38, v39
	v_cndmask_b32_e32 v56, v219, v56, vcc
	v_cmp_gt_u32_e32 vcc, s91, v39
	s_and_b64 vcc, s[66:67], vcc
	v_lshl_or_b32 v54, s69, 4, v46
	s_cmpk_gt_u32 s30, 0x4f
	v_sub_u32_e32 v55, v35, v54
	v_cndmask_b32_e32 v39, v219, v57, vcc
	s_cselect_b64 s[66:67], -1, 0
	v_cmp_gt_u32_e32 vcc, s91, v55
	s_and_b64 vcc, s[66:67], vcc
	v_sub_u32_e32 v55, v54, v35
	v_cndmask_b32_e32 v57, v219, v58, vcc
	v_cmp_lt_u32_e32 vcc, s42, v55
	s_and_b64 vcc, s[66:67], vcc
	v_sub_u32_e32 v55, v36, v54
	v_cndmask_b32_e32 v58, v219, v59, vcc
	v_cmp_gt_u32_e32 vcc, s91, v55
	s_and_b64 vcc, s[66:67], vcc
	v_sub_u32_e32 v54, v38, v54
	v_cndmask_b32_e32 v59, v219, v60, vcc
	v_cmp_gt_u32_e32 vcc, s91, v54
	s_and_b64 vcc, s[66:67], vcc
	v_lshl_or_b32 v54, s88, 4, v46
	s_cmp_gt_u32 s30, 63
	v_sub_u32_e32 v55, v35, v54
	v_cndmask_b32_e32 v60, v219, v61, vcc
	s_cselect_b64 s[66:67], -1, 0
	v_cmp_gt_u32_e32 vcc, s91, v55
	s_and_b64 vcc, s[66:67], vcc
	v_sub_u32_e32 v55, v54, v35
	v_cndmask_b32_e32 v61, v219, v62, vcc
	v_cmp_lt_u32_e32 vcc, s42, v55
	s_and_b64 vcc, s[66:67], vcc
	v_sub_u32_e32 v55, v36, v54
	v_cndmask_b32_e32 v62, v219, v63, vcc
	v_cmp_gt_u32_e32 vcc, s91, v55
	s_and_b64 vcc, s[66:67], vcc
	v_sub_u32_e32 v54, v38, v54
	v_cndmask_b32_e32 v63, v219, v64, vcc
	v_cmp_gt_u32_e32 vcc, s91, v54
	s_and_b64 vcc, s[66:67], vcc
	v_lshl_or_b32 v54, s89, 4, v46
; __device__ __forceinline__ unsigned cvt_pk_bf16(float lo, float hi) { unsigned r; asm volatile("v_cvt_pk_bf16_f32 %0, %1, %2" : "=v"(r) : "v"(lo), "v"(hi)); return r; }
; __device__ __forceinline__ void phase_attn(Frame& F, const Params& p, int j) {
;     ...
;             float m = sink;
; #pragma unroll
;             for (int t = 0; t < 9; ++t)
; #pragma unroll
;                 for (int jj = 0; jj < 4; ++jj) { const int key = (ktb + t) * 16 + fq * 4 + jj, dd = q - key; const bool ok = key >= 0 && dd >= 0 && dd < 128;
;                     s[t][jj] = ok ? s[t][jj] : -1e30f; m = fmaxf(m, s[t][jj]); }
;             m = fmaxf(m, __shfl_xor(m, 16)); m = fmaxf(m, __shfl_xor(m, 32));
;             float l = 0.f; s16x4 pf[9];
; #pragma unroll
;             for (int t = 0; t < 9; ++t) {
;                 float pe[4];
; #pragma unroll
;                 for (int jj = 0; jj < 4; ++jj) { pe[jj] = __expf(s[t][jj] - m); l += pe[jj]; }
;                 u32x2 w; w.x = cvt_pk_bf16(pe[0], pe[1]); w.y = cvt_pk_bf16(pe[2], pe[3]);
;                 pf[t] = __builtin_bit_cast(s16x4, w);
;             }
;             l += __shfl_xor(l, 16); l += __shfl_xor(l, 32);
;             const float rden = 1.0f / (l + __expf(sink - m));
	s_cmp_gt_u32 s30, 47
	v_sub_u32_e32 v55, v35, v54
	v_cndmask_b32_e32 v64, v219, v65, vcc
	s_cselect_b64 s[66:67], -1, 0
	v_cmp_gt_u32_e32 vcc, s91, v55
	s_and_b64 vcc, s[66:67], vcc
	v_sub_u32_e32 v55, v54, v35
	v_cndmask_b32_e32 v65, v219, v74, vcc
	v_cmp_lt_u32_e32 vcc, s42, v55
	s_and_b64 vcc, s[66:67], vcc
	v_sub_u32_e32 v55, v36, v54
	v_cndmask_b32_e32 v74, v219, v75, vcc
	v_cmp_gt_u32_e32 vcc, s91, v55
	s_and_b64 vcc, s[66:67], vcc
	v_sub_u32_e32 v54, v38, v54
	v_cndmask_b32_e32 v75, v219, v76, vcc
	v_cmp_gt_u32_e32 vcc, s91, v54
	s_and_b64 vcc, s[66:67], vcc
	v_lshl_or_b32 v54, s94, 4, v46
	s_cmp_gt_u32 s30, 31
	v_sub_u32_e32 v55, v35, v54
	v_cndmask_b32_e32 v76, v219, v77, vcc
	s_cselect_b64 s[66:67], -1, 0
	v_cmp_gt_u32_e32 vcc, s91, v55
	s_and_b64 vcc, s[66:67], vcc
	v_sub_u32_e32 v55, v54, v35
	v_cndmask_b32_e32 v77, v219, v78, vcc
	v_cmp_lt_u32_e32 vcc, s42, v55
	s_and_b64 vcc, s[66:67], vcc
	v_sub_u32_e32 v55, v36, v54
	v_cndmask_b32_e32 v78, v219, v79, vcc
	v_cmp_gt_u32_e32 vcc, s91, v55
	s_and_b64 vcc, s[66:67], vcc
	v_sub_u32_e32 v54, v38, v54
	v_cndmask_b32_e32 v79, v219, v80, vcc
	v_cmp_gt_u32_e32 vcc, s91, v54
	v_lshl_or_b32 v54, s95, 4, v46
	v_max3_f32 v33, v33, v37, v30
	s_and_b64 vcc, s[66:67], vcc
	v_sub_u32_e32 v55, v35, v54
	v_max3_f32 v33, v33, v40, v41
	v_cndmask_b32_e32 v80, v219, v81, vcc
	v_cmp_gt_u32_e32 vcc, s91, v55
	v_max3_f32 v33, v33, v56, v39
	s_and_b64 vcc, s[10:11], vcc
	v_sub_u32_e32 v55, v54, v35
	v_max3_f32 v33, v33, v57, v58
	v_cndmask_b32_e32 v81, v219, v82, vcc
	v_cmp_lt_u32_e32 vcc, s42, v55
	v_max3_f32 v33, v33, v59, v60
	s_and_b64 vcc, s[10:11], vcc
	v_sub_u32_e32 v55, v36, v54
	v_max3_f32 v33, v33, v61, v62
	v_cndmask_b32_e32 v82, v219, v83, vcc
	v_cmp_gt_u32_e32 vcc, s91, v55
	v_max3_f32 v33, v33, v63, v64
	s_and_b64 vcc, s[10:11], vcc
	v_sub_u32_e32 v54, v38, v54
	v_max3_f32 v33, v33, v65, v74
	v_cndmask_b32_e32 v83, v219, v84, vcc
	v_cmp_gt_u32_e32 vcc, s91, v54
	v_or_b32_e32 v54, s49, v46
	v_max3_f32 v33, v33, v75, v76
	s_and_b64 vcc, s[10:11], vcc
	v_sub_u32_e32 v55, v35, v54
	v_max3_f32 v33, v33, v77, v78
	v_cndmask_b32_e32 v84, v219, v85, vcc
	v_cmp_gt_u32_e32 vcc, s91, v55
	v_sub_u32_e32 v35, v54, v35
	v_max3_f32 v33, v33, v79, v80
	v_cndmask_b32_e32 v85, v219, v86, vcc
	v_cmp_lt_u32_e32 vcc, s42, v35
	v_sub_u32_e32 v36, v36, v54
	v_max3_f32 v33, v33, v81, v82
	v_cndmask_b32_e32 v35, v219, v87, vcc
	v_cmp_gt_u32_e32 vcc, s91, v36
	v_sub_u32_e32 v36, v38, v54
	v_max3_f32 v33, v33, v83, v84
	v_cndmask_b32_e32 v86, v219, v88, vcc
	v_cmp_gt_u32_e32 vcc, s91, v36
	v_max3_f32 v33, v33, v85, v35
	v_cndmask_b32_e64 v26, v219, v26, s[2:3]
	v_cndmask_b32_e32 v87, v219, v89, vcc
	v_max3_f32 v33, v33, v86, v87
	v_cndmask_b32_e64 v27, v219, v27, s[4:5]
	v_max3_f32 v33, v33, v26, v27
	v_cndmask_b32_e64 v88, v219, v28, s[6:7]
	v_cndmask_b32_e64 v89, v219, v29, s[8:9]
	v_max3_f32 v28, v33, v88, v89
	ds_bpermute_b32 v29, v67, v28
	s_lshl_b32 s30, s64, 5
	s_sub_i32 s30, s30, s26
	s_lshr_b32 s49, s29, 4
	s_add_i32 s64, s49, -8
	s_waitcnt lgkmcnt(0)
	v_max_f32_e32 v29, v29, v29
	v_max_f32_e32 v28, v28, v29
	ds_bpermute_b32 v29, v68, v28
	s_add_i32 s66, s49, -7
	s_add_i32 s67, s49, -6
	s_add_i32 s68, s49, -5
	s_add_i32 s69, s49, -4
	s_waitcnt lgkmcnt(0)
	v_max_f32_e32 v29, v29, v29
	v_max_f32_e32 v90, v28, v29
	v_mul_f32_e32 v136, 0xbfb8aa3b, v90
	v_fmamk_f32 v28, v31, 0x3fb8aa3b, v136
	v_exp_f32_e32 v28, v28
	v_fmamk_f32 v31, v32, 0x3fb8aa3b, v136
	v_exp_f32_e32 v31, v31
	v_fmamk_f32 v32, v37, 0x3fb8aa3b, v136
	v_exp_f32_e32 v32, v32
	v_fmamk_f32 v30, v30, 0x3fb8aa3b, v136
	v_exp_f32_e32 v30, v30
	v_add_f32_e32 v29, 0, v28
	v_add_f32_e32 v29, v31, v29
	v_add_f32_e32 v29, v32, v29
	v_cvt_pk_bf16_f32 v54, v28, v31
	v_add_f32_e32 v29, v30, v29
	v_cvt_pk_bf16_f32 v55, v32, v30
	v_fmamk_f32 v28, v40, 0x3fb8aa3b, v136
	v_exp_f32_e32 v28, v28
	v_fmamk_f32 v30, v41, 0x3fb8aa3b, v136
	v_exp_f32_e32 v30, v30
	v_fmamk_f32 v31, v56, 0x3fb8aa3b, v136
	v_exp_f32_e32 v31, v31
	v_fmamk_f32 v32, v39, 0x3fb8aa3b, v136
	v_exp_f32_e32 v32, v32
	v_add_f32_e32 v29, v28, v29
	v_cvt_pk_bf16_f32 v40, v28, v30
	v_add_f32_e32 v29, v30, v29
	v_fmamk_f32 v28, v57, 0x3fb8aa3b, v136
	v_add_f32_e32 v29, v31, v29
	v_cvt_pk_bf16_f32 v41, v31, v32
	v_exp_f32_e32 v28, v28
	v_fmamk_f32 v30, v58, 0x3fb8aa3b, v136
	v_add_f32_e32 v29, v32, v29
	v_exp_f32_e32 v30, v30
	v_fmamk_f32 v31, v59, 0x3fb8aa3b, v136
	v_exp_f32_e32 v31, v31
	v_fmamk_f32 v32, v60, 0x3fb8aa3b, v136
	v_exp_f32_e32 v32, v32
	v_add_f32_e32 v29, v28, v29
	v_cvt_pk_bf16_f32 v56, v28, v30
	v_add_f32_e32 v29, v30, v29
	v_fmamk_f32 v28, v61, 0x3fb8aa3b, v136
	v_add_f32_e32 v29, v31, v29
	v_cvt_pk_bf16_f32 v57, v31, v32
	v_exp_f32_e32 v28, v28
	v_fmamk_f32 v30, v62, 0x3fb8aa3b, v136
	v_add_f32_e32 v29, v32, v29
	v_exp_f32_e32 v30, v30
	v_fmamk_f32 v31, v63, 0x3fb8aa3b, v136
	v_exp_f32_e32 v31, v31
	v_fmamk_f32 v32, v64, 0x3fb8aa3b, v136
	v_exp_f32_e32 v32, v32
	v_add_f32_e32 v29, v28, v29
	v_cvt_pk_bf16_f32 v38, v28, v30
	v_add_f32_e32 v29, v30, v29
	v_fmamk_f32 v28, v65, 0x3fb8aa3b, v136
	v_add_f32_e32 v29, v31, v29
	v_cvt_pk_bf16_f32 v39, v31, v32
	v_exp_f32_e32 v28, v28
	v_fmamk_f32 v30, v74, 0x3fb8aa3b, v136
	v_add_f32_e32 v29, v32, v29
	v_exp_f32_e32 v30, v30
	v_fmamk_f32 v31, v75, 0x3fb8aa3b, v136
	v_exp_f32_e32 v31, v31
	v_fmamk_f32 v32, v76, 0x3fb8aa3b, v136
	v_exp_f32_e32 v32, v32
	v_add_f32_e32 v29, v28, v29
	v_cvt_pk_bf16_f32 v36, v28, v30
	v_add_f32_e32 v29, v30, v29
	v_fmamk_f32 v28, v77, 0x3fb8aa3b, v136
	v_add_f32_e32 v29, v31, v29
	v_cvt_pk_bf16_f32 v37, v31, v32
	v_exp_f32_e32 v28, v28
	v_fmamk_f32 v30, v78, 0x3fb8aa3b, v136
	v_add_f32_e32 v29, v32, v29
; #define LAS __attribute__((address_space(3)))
; __device__ __forceinline__ unsigned cvt_pk_bf16(float lo, float hi) { unsigned r; asm volatile("v_cvt_pk_bf16_f32 %0, %1, %2" : "=v"(r) : "v"(lo), "v"(hi)); return r; }
; __device__ __forceinline__ void phase_attn(Frame& F, const Params& p, int j) {
;     ...
;             float l = 0.f; s16x4 pf[9];
; #pragma unroll
;             for (int t = 0; t < 9; ++t) {
;                 float pe[4];
; #pragma unroll
;                 for (int jj = 0; jj < 4; ++jj) { pe[jj] = __expf(s[t][jj] - m); l += pe[jj]; }
;                 u32x2 w; w.x = cvt_pk_bf16(pe[0], pe[1]); w.y = cvt_pk_bf16(pe[2], pe[3]);
;                 pf[t] = __builtin_bit_cast(s16x4, w);
;             }
;             l += __shfl_xor(l, 16); l += __shfl_xor(l, 32);
;             const float rden = 1.0f / (l + __expf(sink - m));
;             f32x4 o[4];
; #pragma unroll
;             for (int dt = 0; dt < 4; ++dt) o[dt] = (f32x4){0.f, 0.f, 0.f, 0.f};
; #pragma unroll
;             for (int t = 0; t < 9; ++t) {
;                 const int kt = ktb + t > 0 ? ktb + t : 0;
; #pragma unroll
;                 for (int dt = 0; dt < 4; ++dt) {
;                     const s16x4 vf = *(const LAS s16x4*)(F.lds + VOFF + (dt * 16 + fr) * VSTR + (kt * 16 - k_lo + fq * 4) * 2);
;                     o[dt] = __builtin_amdgcn_mfma_f32_16x16x16bf16_1k(vf, pf[t], o[dt], 0, 0, 0);
;                 }
;             }
	v_exp_f32_e32 v30, v30
	v_fmamk_f32 v31, v79, 0x3fb8aa3b, v136
	v_exp_f32_e32 v31, v31
	v_fmamk_f32 v32, v80, 0x3fb8aa3b, v136
	v_exp_f32_e32 v33, v32
	v_add_f32_e32 v29, v28, v29
	v_add_f32_e32 v29, v30, v29
	v_cvt_pk_bf16_f32 v32, v28, v30
	v_add_f32_e32 v29, v31, v29
	v_fmamk_f32 v28, v81, 0x3fb8aa3b, v136
	v_add_f32_e32 v29, v33, v29
	v_cvt_pk_bf16_f32 v33, v31, v33
	v_exp_f32_e32 v28, v28
	v_fmamk_f32 v30, v82, 0x3fb8aa3b, v136
	v_exp_f32_e32 v30, v30
	v_fmamk_f32 v31, v83, 0x3fb8aa3b, v136
	v_exp_f32_e32 v31, v31
	v_fmamk_f32 v58, v84, 0x3fb8aa3b, v136
	v_exp_f32_e32 v58, v58
	v_add_f32_e32 v29, v28, v29
	v_add_f32_e32 v29, v30, v29
	v_cvt_pk_bf16_f32 v30, v28, v30
	v_add_f32_e32 v29, v31, v29
	v_fmamk_f32 v28, v85, 0x3fb8aa3b, v136
	v_add_f32_e32 v29, v58, v29
	v_cvt_pk_bf16_f32 v31, v31, v58
	v_exp_f32_e32 v28, v28
	v_fmamk_f32 v35, v35, 0x3fb8aa3b, v136
	v_exp_f32_e32 v35, v35
	v_fmamk_f32 v58, v86, 0x3fb8aa3b, v136
	v_exp_f32_e32 v58, v58
	v_fmamk_f32 v59, v87, 0x3fb8aa3b, v136
	v_exp_f32_e32 v59, v59
	v_add_f32_e32 v29, v28, v29
	v_add_f32_e32 v29, v35, v29
	v_add_f32_e32 v29, v58, v29
	v_fmamk_f32 v26, v26, 0x3fb8aa3b, v136
	v_add_f32_e32 v60, v59, v29
	v_cvt_pk_bf16_f32 v28, v28, v35
	v_cvt_pk_bf16_f32 v29, v58, v59
	v_exp_f32_e32 v26, v26
	v_fmamk_f32 v27, v27, 0x3fb8aa3b, v136
	v_exp_f32_e32 v27, v27
	v_fmamk_f32 v58, v88, 0x3fb8aa3b, v136
	v_exp_f32_e32 v58, v58
	v_fmamk_f32 v59, v89, 0x3fb8aa3b, v136
	v_exp_f32_e32 v59, v59
	v_add_f32_e32 v35, v26, v60
	v_add_f32_e32 v35, v27, v35
	v_add_f32_e32 v35, v58, v35
	v_add_f32_e32 v35, v59, v35
	v_cvt_pk_bf16_f32 v26, v26, v27
	v_cvt_pk_bf16_f32 v27, v58, v59
	ds_bpermute_b32 v58, v67, v35
	v_add_u32_e32 v78, s30, v70
	ds_read_b64 v[62:63], v78 offset:36352
	ds_read_b64 v[74:75], v78 offset:42752
	s_lshl_b32 s30, s59, 5
	s_waitcnt lgkmcnt(2)
	v_add_f32_e32 v35, v35, v58
	ds_bpermute_b32 v58, v68, v35
	s_sub_i32 s30, s30, s26
	v_add_u32_e32 v82, s30, v70
	s_waitcnt lgkmcnt(2)
	v_mfma_f32_16x16x16_bf16 v[62:65], v[62:63], v[54:55], 0
	s_waitcnt lgkmcnt(0)
	v_add_f32_e32 v35, v35, v58
	v_fmamk_f32 v58, v73, 0x3fb8aa3b, v136
	v_exp_f32_e32 v58, v58
	v_mfma_f32_16x16x16_bf16 v[74:77], v[74:75], v[54:55], 0
	s_lshl_b32 s30, s39, 5
	s_sub_i32 s30, s30, s26
	v_add_f32_e32 v35, v58, v35
	ds_read_b64 v[58:59], v78 offset:29952
	ds_read_b64 v[78:79], v78 offset:49152
	s_waitcnt lgkmcnt(1)
	v_mfma_f32_16x16x16_bf16 v[58:61], v[58:59], v[54:55], 0
	s_max_i32 s59, s64, 0
	s_max_i32 s39, s66, 0
	s_add_i32 s88, s49, -3
	s_waitcnt lgkmcnt(0)
	v_mfma_f32_16x16x16_bf16 v[78:81], v[78:79], v[54:55], 0
	ds_read_b64 v[54:55], v82 offset:29952
	s_waitcnt lgkmcnt(0)
	v_mfma_f32_16x16x16_bf16 v[58:61], v[54:55], v[40:41], v[58:61]
	ds_read_b64 v[54:55], v82 offset:36352
	s_waitcnt lgkmcnt(0)
	v_mfma_f32_16x16x16_bf16 v[62:65], v[54:55], v[40:41], v[62:65]
	ds_read_b64 v[54:55], v82 offset:42752
	s_waitcnt lgkmcnt(0)
	v_mfma_f32_16x16x16_bf16 v[74:77], v[54:55], v[40:41], v[74:77]
	ds_read_b64 v[54:55], v82 offset:49152
	s_waitcnt lgkmcnt(0)
	v_mfma_f32_16x16x16_bf16 v[78:81], v[54:55], v[40:41], v[78:81]
	v_add_u32_e32 v54, s30, v70
	ds_read_b64 v[40:41], v54 offset:29952
	s_lshl_b32 s30, s38, 5
	s_waitcnt lgkmcnt(0)
	v_mfma_f32_16x16x16_bf16 v[58:61], v[40:41], v[56:57], v[58:61]
	ds_read_b64 v[40:41], v54 offset:36352
	s_sub_i32 s30, s30, s26
	s_max_i32 s38, s67, 0
	s_waitcnt lgkmcnt(0)
	v_mfma_f32_16x16x16_bf16 v[62:65], v[40:41], v[56:57], v[62:65]
	ds_read_b64 v[40:41], v54 offset:42752
	s_waitcnt lgkmcnt(0)
	v_mfma_f32_16x16x16_bf16 v[74:77], v[40:41], v[56:57], v[74:77]
	ds_read_b64 v[40:41], v54 offset:49152
	s_waitcnt lgkmcnt(0)
	v_mfma_f32_16x16x16_bf16 v[54:57], v[40:41], v[56:57], v[78:81]
	s_nop 2
	v_add_u32_e32 v78, s30, v70
	ds_read_b64 v[40:41], v78 offset:29952
	s_lshl_b32 s30, s37, 5
	s_waitcnt lgkmcnt(0)
	v_mfma_f32_16x16x16_bf16 v[58:61], v[40:41], v[38:39], v[58:61]
	ds_read_b64 v[40:41], v78 offset:36352
	s_sub_i32 s30, s30, s26
	s_max_i32 s37, s68, 0
	s_waitcnt lgkmcnt(0)
	v_mfma_f32_16x16x16_bf16 v[62:65], v[40:41], v[38:39], v[62:65]
	ds_read_b64 v[40:41], v78 offset:42752
	s_waitcnt lgkmcnt(0)
	v_mfma_f32_16x16x16_bf16 v[74:77], v[40:41], v[38:39], v[74:77]
	ds_read_b64 v[40:41], v78 offset:49152
	v_add_u32_e32 v78, s30, v70
	s_lshl_b32 s30, s36, 5
	s_waitcnt lgkmcnt(0)
	v_mfma_f32_16x16x16_bf16 v[38:41], v[40:41], v[38:39], v[54:57]
	s_nop 2
	ds_read_b64 v[54:55], v78 offset:29952
	s_sub_i32 s30, s30, s26
	s_max_i32 s36, s69, 0
	s_waitcnt lgkmcnt(0)
	v_mfma_f32_16x16x16_bf16 v[54:57], v[54:55], v[36:37], v[58:61]
	s_nop 2
	ds_read_b64 v[58:59], v78 offset:36352
	s_waitcnt lgkmcnt(0)
	v_mfma_f32_16x16x16_bf16 v[58:61], v[58:59], v[36:37], v[62:65]
	s_nop 2
	ds_read_b64 v[62:63], v78 offset:42752
	s_waitcnt lgkmcnt(0)
	v_mfma_f32_16x16x16_bf16 v[62:65], v[62:63], v[36:37], v[74:77]
	s_nop 2
	ds_read_b64 v[74:75], v78 offset:49152
	s_waitcnt lgkmcnt(0)
	v_mfma_f32_16x16x16_bf16 v[36:39], v[74:75], v[36:37], v[38:41]
	v_add_u32_e32 v74, s30, v70
	s_nop 1
	ds_read_b64 v[40:41], v74 offset:29952
	s_lshl_b32 s30, s35, 5
	s_waitcnt lgkmcnt(0)
	v_mfma_f32_16x16x16_bf16 v[54:57], v[40:41], v[32:33], v[54:57]
	ds_read_b64 v[40:41], v74 offset:36352
	s_sub_i32 s30, s30, s26
	s_max_i32 s35, s88, 0
	s_waitcnt lgkmcnt(0)
	v_mfma_f32_16x16x16_bf16 v[58:61], v[40:41], v[32:33], v[58:61]
	ds_read_b64 v[40:41], v74 offset:42752
	s_waitcnt lgkmcnt(0)
	v_mfma_f32_16x16x16_bf16 v[62:65], v[40:41], v[32:33], v[62:65]
	ds_read_b64 v[40:41], v74 offset:49152
	s_waitcnt lgkmcnt(0)
	v_mfma_f32_16x16x16_bf16 v[36:39], v[40:41], v[32:33], v[36:39]
	v_add_u32_e32 v40, s30, v70
	ds_read_b64 v[32:33], v40 offset:29952
	s_lshl_b32 s30, s34, 5
	s_waitcnt lgkmcnt(0)
; #define LAS __attribute__((address_space(3)))
; __device__ __forceinline__ unsigned cvt_pk_bf16(float lo, float hi) { unsigned r; asm volatile("v_cvt_pk_bf16_f32 %0, %1, %2" : "=v"(r) : "v"(lo), "v"(hi)); return r; }
; __device__ __forceinline__ void phase_attn(Frame& F, const Params& p, int j) {
;     ...
; #pragma unroll
;             for (int t = 0; t < 9; ++t) {
;                 const int kt = ktb + t > 0 ? ktb + t : 0;
;                 const LAS unsigned char* kp = F.lds + (kt * 16 - k_lo + fr) * KSTR + fq * 16;
;                 const bf16x8 kf0 = *(const LAS bf16x8*)kp, kf1 = *(const LAS bf16x8*)(kp + 64);
;                 s[t] = (f32x4){0.f, 0.f, 0.f, 0.f};
;                 s[t] = __builtin_amdgcn_mfma_f32_16x16x32_bf16(kf0, qf0, s[t], 0, 0, 0);
;                 s[t] = __builtin_amdgcn_mfma_f32_16x16x32_bf16(kf1, qf1, s[t], 0, 0, 0);
;             }
;     ...
; #pragma unroll
;             for (int t = 0; t < 9; ++t) {
;                 const int kt = ktb + t > 0 ? ktb + t : 0;
; #pragma unroll
;                 for (int dt = 0; dt < 4; ++dt) {
;                     const s16x4 vf = *(const LAS s16x4*)(F.lds + VOFF + (dt * 16 + fr) * VSTR + (kt * 16 - k_lo + fq * 4) * 2);
;                     o[dt] = __builtin_amdgcn_mfma_f32_16x16x16bf16_1k(vf, pf[t], o[dt], 0, 0, 0);
;                 }
;             }
;             bf16_t* op = F.OB + (size_t)qrow * D + h * 64 + fq * 4;
; #pragma unroll
;             for (int dt = 0; dt < 4; ++dt) { u32x2 w; w.x = cvt_pk_bf16(o[dt][0] * rden, o[dt][1] * rden); w.y = cvt_pk_bf16(o[dt][2] * rden, o[dt][3] * rden); *(u32x2*)(op + dt * 16) = w; }
	v_mfma_f32_16x16x16_bf16 v[54:57], v[32:33], v[30:31], v[54:57]
	ds_read_b64 v[32:33], v40 offset:36352
	s_sub_i32 s30, s30, s26
	v_add_u32_e32 v74, s30, v70
	s_waitcnt lgkmcnt(0)
	v_mfma_f32_16x16x16_bf16 v[58:61], v[32:33], v[30:31], v[58:61]
	ds_read_b64 v[32:33], v40 offset:42752
	s_add_i32 s34, s49, -2
	s_lshl_b32 s89, s34, 4
	s_waitcnt lgkmcnt(0)
	v_mfma_f32_16x16x16_bf16 v[62:65], v[32:33], v[30:31], v[62:65]
	ds_read_b64 v[32:33], v40 offset:49152
	ds_read_b64 v[40:41], v74 offset:36352
	s_waitcnt lgkmcnt(1)
	v_mfma_f32_16x16x16_bf16 v[30:33], v[32:33], v[30:31], v[36:39]
	s_nop 2
	ds_read_b64 v[36:37], v74 offset:29952
	s_waitcnt lgkmcnt(0)
	v_mfma_f32_16x16x16_bf16 v[36:39], v[36:37], v[28:29], v[54:57]
	v_mfma_f32_16x16x16_bf16 v[54:57], v[40:41], v[28:29], v[58:61]
	ds_read_b64 v[40:41], v74 offset:42752
	s_waitcnt lgkmcnt(0)
	v_mfma_f32_16x16x16_bf16 v[58:61], v[40:41], v[28:29], v[62:65]
	ds_read_b64 v[40:41], v74 offset:49152
	s_waitcnt lgkmcnt(0)
	v_mfma_f32_16x16x16_bf16 v[28:31], v[40:41], v[28:29], v[30:33]
	v_lshl_add_u32 v40, s31, 1, v70
	s_nop 1
	ds_read_b64 v[32:33], v40 offset:29952
	s_waitcnt lgkmcnt(0)
	v_mfma_f32_16x16x16_bf16 v[36:39], v[32:33], v[26:27], v[36:39]
	ds_read_b64 v[32:33], v40 offset:36352
	s_waitcnt lgkmcnt(0)
	v_mfma_f32_16x16x16_bf16 v[54:57], v[32:33], v[26:27], v[54:57]
	ds_read_b64 v[32:33], v40 offset:42752
	s_waitcnt lgkmcnt(0)
	v_mfma_f32_16x16x16_bf16 v[58:61], v[32:33], v[26:27], v[58:61]
	ds_read_b64 v[32:33], v40 offset:49152
	s_waitcnt lgkmcnt(0)
	v_mfma_f32_16x16x16_bf16 v[26:29], v[32:33], v[26:27], v[28:31]
	s_nop 2
	v_div_scale_f32 v30, s[30:31], v35, v35, 1.0
	v_rcp_f32_e32 v31, v30
	s_lshl_b32 s30, s59, 4
	s_sub_i32 s30, s30, s27
	v_fma_f32 v32, -v30, v31, 1.0
	v_fmac_f32_e32 v31, v32, v31
	v_div_scale_f32 v32, vcc, 1.0, v35, 1.0
	v_mul_f32_e32 v33, v32, v31
	v_fma_f32 v40, -v30, v33, v32
	v_fmac_f32_e32 v33, v40, v31
	v_fma_f32 v30, -v30, v33, v32
	v_div_fmas_f32 v30, v30, v31, v33
	v_div_fixup_f32 v40, v30, v35, 1.0
	v_ashrrev_i32_e32 v35, 31, v34
	v_lshlrev_b64 v[30:31], 12, v[34:35]
	v_lshl_add_u64 v[30:31], s[86:87], 0, v[30:31]
	v_mul_f32_e32 v32, v40, v36
	v_mul_f32_e32 v33, v40, v37
	v_lshl_add_u64 v[30:31], v[30:31], 0, s[82:83]
	v_cvt_pk_bf16_f32 v32, v32, v33
	v_mul_f32_e32 v33, v40, v38
	v_lshl_add_u64 v[30:31], v[30:31], 0, v[168:169]
	v_mul_f32_e32 v34, v40, v39
	v_cvt_pk_bf16_f32 v33, v33, v34
	global_store_dwordx2 v[30:31], v[32:33], off
	v_mul_f32_e32 v32, v40, v54
	v_mul_f32_e32 v33, v40, v55
	v_cvt_pk_bf16_f32 v32, v32, v33
	v_mul_f32_e32 v33, v40, v56
	v_mul_f32_e32 v34, v40, v57
	v_cvt_pk_bf16_f32 v33, v33, v34
	global_store_dwordx2 v[30:31], v[32:33], off offset:32
	v_mul_f32_e32 v32, v40, v58
	v_mul_f32_e32 v33, v40, v59
	v_cvt_pk_bf16_f32 v32, v32, v33
	v_mul_f32_e32 v33, v40, v60
	v_mul_f32_e32 v26, v40, v26
	v_mul_f32_e32 v27, v40, v27
	v_mul_f32_e32 v34, v40, v61
	v_cvt_pk_bf16_f32 v33, v33, v34
	global_store_dwordx2 v[30:31], v[32:33], off offset:64
	v_cvt_pk_bf16_f32 v26, v26, v27
	v_mul_f32_e32 v27, v40, v28
	v_mul_f32_e32 v28, v40, v29
	v_cvt_pk_bf16_f32 v27, v27, v28
	v_or_b32_e32 v28, s30, v126
	global_store_dwordx2 v[30:31], v[26:27], off offset:96
	v_mad_u64_u32 v[32:33], s[30:31], v28, s80, v[48:49]
	ds_read_b128 v[28:31], v32
	ds_read_b128 v[32:35], v32 offset:64
	s_waitcnt vmcnt(13) lgkmcnt(1)
	v_mfma_f32_16x16x32_bf16 v[28:31], v[28:31], v[22:25], 0
	s_lshl_b32 s30, s39, 4
	s_sub_i32 s30, s30, s27
	v_or_b32_e32 v27, s29, v126
	s_waitcnt vmcnt(12) lgkmcnt(0)
	v_mfma_f32_16x16x32_bf16 v[28:31], v[32:35], v[18:21], v[28:31]
	v_or_b32_e32 v32, s30, v126
	v_mad_u64_u32 v[36:37], s[30:31], v32, s80, v[48:49]
	ds_read_b128 v[32:35], v36
	ds_read_b128 v[36:39], v36 offset:64
	s_waitcnt lgkmcnt(1)
	v_mfma_f32_16x16x32_bf16 v[32:35], v[32:35], v[22:25], 0
	s_lshl_b32 s30, s38, 4
	s_sub_i32 s30, s30, s27
	v_add_u32_e32 v26, s25, v27
	s_waitcnt lgkmcnt(0)
	v_mfma_f32_16x16x32_bf16 v[32:35], v[36:39], v[18:21], v[32:35]
	v_or_b32_e32 v36, s30, v126
	v_mad_u64_u32 v[40:41], s[30:31], v36, s80, v[48:49]
	ds_read_b128 v[36:39], v40
	ds_read_b128 v[54:57], v40 offset:64
	s_waitcnt lgkmcnt(1)
	v_mfma_f32_16x16x32_bf16 v[36:39], v[36:39], v[22:25], 0
	s_lshl_b32 s30, s37, 4
	s_sub_i32 s30, s30, s27
	v_or_b32_e32 v40, s30, v126
	v_mad_u64_u32 v[40:41], s[30:31], v40, s80, v[48:49]
	s_waitcnt lgkmcnt(0)
	v_mfma_f32_16x16x32_bf16 v[36:39], v[54:57], v[18:21], v[36:39]
	ds_read_b128 v[54:57], v40
	ds_read_b128 v[58:61], v40 offset:64
	s_lshl_b32 s30, s36, 4
	s_sub_i32 s30, s30, s27
	s_waitcnt lgkmcnt(1)
	v_mfma_f32_16x16x32_bf16 v[54:57], v[54:57], v[22:25], 0
	v_or_b32_e32 v40, s30, v126
	v_mad_u64_u32 v[40:41], s[30:31], v40, s80, v[48:49]
	s_waitcnt lgkmcnt(0)
	v_mfma_f32_16x16x32_bf16 v[54:57], v[58:61], v[18:21], v[54:57]
	ds_read_b128 v[58:61], v40
	ds_read_b128 v[62:65], v40 offset:64
	s_lshl_b32 s30, s35, 4
	s_sub_i32 s30, s30, s27
	s_waitcnt lgkmcnt(1)
	v_mfma_f32_16x16x32_bf16 v[58:61], v[58:61], v[22:25], 0
	v_or_b32_e32 v40, s30, v126
	v_mad_u64_u32 v[40:41], s[30:31], v40, s80, v[48:49]
	s_waitcnt lgkmcnt(0)
	v_mfma_f32_16x16x32_bf16 v[58:61], v[62:65], v[18:21], v[58:61]
	ds_read_b128 v[62:65], v40
	ds_read_b128 v[74:77], v40 offset:64
	s_sub_i32 s30, s89, s27
	v_or_b32_e32 v40, s30, v126
	s_waitcnt lgkmcnt(1)
	v_mfma_f32_16x16x32_bf16 v[62:65], v[62:65], v[22:25], 0
	v_mad_i32_i24 v40, v40, s80, v48
	s_add_i32 s31, s49, -1
	s_lshl_b32 s49, s31, 4
	s_waitcnt lgkmcnt(0)
	v_mfma_f32_16x16x32_bf16 v[62:65], v[74:77], v[18:21], v[62:65]
	ds_read_b128 v[74:77], v40
	ds_read_b128 v[78:81], v40 offset:64
	s_sub_i32 s30, s49, s27
	v_or_b32_e32 v40, s30, v126
	s_waitcnt lgkmcnt(1)
; #define LAS __attribute__((address_space(3)))
; __device__ __forceinline__ void phase_attn(Frame& F, const Params& p, int j) {
;     ...
; #pragma unroll
;             for (int t = 0; t < 9; ++t) {
;                 const int kt = ktb + t > 0 ? ktb + t : 0;
;                 const LAS unsigned char* kp = F.lds + (kt * 16 - k_lo + fr) * KSTR + fq * 16;
;                 const bf16x8 kf0 = *(const LAS bf16x8*)kp, kf1 = *(const LAS bf16x8*)(kp + 64);
;                 s[t] = (f32x4){0.f, 0.f, 0.f, 0.f};
;                 s[t] = __builtin_amdgcn_mfma_f32_16x16x32_bf16(kf0, qf0, s[t], 0, 0, 0);
;                 s[t] = __builtin_amdgcn_mfma_f32_16x16x32_bf16(kf1, qf1, s[t], 0, 0, 0);
;             }
;             float m = sink;
; #pragma unroll
;             for (int t = 0; t < 9; ++t)
; #pragma unroll
;                 for (int jj = 0; jj < 4; ++jj) { const int key = (ktb + t) * 16 + fq * 4 + jj, dd = q - key; const bool ok = key >= 0 && dd >= 0 && dd < 128;
;                     s[t][jj] = ok ? s[t][jj] : -1e30f; m = fmaxf(m, s[t][jj]); }
;             m = fmaxf(m, __shfl_xor(m, 16)); m = fmaxf(m, __shfl_xor(m, 32));
	v_mfma_f32_16x16x32_bf16 v[74:77], v[74:77], v[22:25], 0
	v_mad_i32_i24 v40, v40, s80, v48
	s_sub_i32 s30, s29, s27
	s_cmpk_gt_u32 s29, 0x70
	s_waitcnt lgkmcnt(0)
	v_mfma_f32_16x16x32_bf16 v[74:77], v[78:81], v[18:21], v[74:77]
	ds_read_b128 v[78:81], v40
	ds_read_b128 v[82:85], v40 offset:64
	v_or_b32_e32 v40, s30, v126
	v_mad_i32_i24 v40, v40, s80, v48
	s_waitcnt lgkmcnt(1)
	v_mfma_f32_16x16x32_bf16 v[78:81], v[78:81], v[22:25], 0
	s_waitcnt lgkmcnt(0)
	v_mfma_f32_16x16x32_bf16 v[78:81], v[82:85], v[18:21], v[78:81]
	ds_read_b128 v[82:85], v40
	ds_read_b128 v[86:89], v40 offset:64
	s_waitcnt lgkmcnt(1)
	v_mfma_f32_16x16x32_bf16 v[22:25], v[82:85], v[22:25], 0
	s_waitcnt lgkmcnt(0)
	v_mfma_f32_16x16x32_bf16 v[18:21], v[86:89], v[18:21], v[22:25]
	s_nop 5
	v_lshl_or_b32 v22, s64, 4, v46
	v_sub_u32_e32 v23, v27, v22
	s_cselect_b64 s[64:65], -1, 0
	v_cmp_gt_u32_e32 vcc, s91, v23
	s_and_b64 vcc, s[64:65], vcc
	v_sub_u32_e32 v24, v22, v27
	v_cndmask_b32_e32 v23, v219, v28, vcc
	v_cmp_lt_u32_e32 vcc, s42, v24
	s_and_b64 vcc, s[64:65], vcc
	v_add_u32_e32 v28, -2, v27
	v_cndmask_b32_e32 v24, v219, v29, vcc
	v_sub_u32_e32 v29, v28, v22
	v_cmp_gt_u32_e32 vcc, s91, v29
	s_and_b64 vcc, s[64:65], vcc
	v_max3_f32 v25, v73, v23, v24
	v_cndmask_b32_e32 v29, v219, v30, vcc
	v_add_u32_e32 v30, -3, v27
	v_sub_u32_e32 v22, v30, v22
	v_cmp_gt_u32_e32 vcc, s91, v22
	s_and_b64 vcc, s[64:65], vcc
	s_cmpk_gt_u32 s29, 0x60
	v_cndmask_b32_e32 v22, v219, v31, vcc
	v_lshl_or_b32 v31, s66, 4, v46
	v_sub_u32_e32 v40, v27, v31
	s_cselect_b64 s[64:65], -1, 0
	v_cmp_gt_u32_e32 vcc, s91, v40
	s_and_b64 vcc, s[64:65], vcc
	v_sub_u32_e32 v40, v31, v27
	v_cndmask_b32_e32 v32, v219, v32, vcc
	v_cmp_lt_u32_e32 vcc, s42, v40
	s_and_b64 vcc, s[64:65], vcc
	v_sub_u32_e32 v40, v28, v31
	v_cndmask_b32_e32 v33, v219, v33, vcc
	v_cmp_gt_u32_e32 vcc, s91, v40
	s_and_b64 vcc, s[64:65], vcc
	v_sub_u32_e32 v31, v30, v31
	v_cndmask_b32_e32 v40, v219, v34, vcc
	v_cmp_gt_u32_e32 vcc, s91, v31
	s_and_b64 vcc, s[64:65], vcc
	v_lshl_or_b32 v34, s67, 4, v46
	v_cndmask_b32_e32 v31, v219, v35, vcc
	s_cmpk_gt_u32 s29, 0x50
	v_sub_u32_e32 v35, v27, v34
	s_cselect_b64 s[64:65], -1, 0
	v_cmp_gt_u32_e32 vcc, s91, v35
	s_and_b64 vcc, s[64:65], vcc
	v_sub_u32_e32 v35, v34, v27
	v_cndmask_b32_e32 v36, v219, v36, vcc
	v_cmp_lt_u32_e32 vcc, s42, v35
	s_and_b64 vcc, s[64:65], vcc
	v_sub_u32_e32 v35, v28, v34
	v_cndmask_b32_e32 v37, v219, v37, vcc
	v_cmp_gt_u32_e32 vcc, s91, v35
	s_and_b64 vcc, s[64:65], vcc
	v_sub_u32_e32 v34, v30, v34
	v_cndmask_b32_e32 v38, v219, v38, vcc
	v_cmp_gt_u32_e32 vcc, s91, v34
	s_and_b64 vcc, s[64:65], vcc
	v_lshl_or_b32 v34, s68, 4, v46
	s_cmp_gt_u32 s29, 64
	v_sub_u32_e32 v35, v27, v34
	v_cndmask_b32_e32 v39, v219, v39, vcc
	s_cselect_b64 s[64:65], -1, 0
	v_cmp_gt_u32_e32 vcc, s91, v35
	s_and_b64 vcc, s[64:65], vcc
	v_sub_u32_e32 v35, v34, v27
	v_cndmask_b32_e32 v41, v219, v54, vcc
	v_cmp_lt_u32_e32 vcc, s42, v35
	s_and_b64 vcc, s[64:65], vcc
	v_sub_u32_e32 v35, v28, v34
	v_cndmask_b32_e32 v54, v219, v55, vcc
	v_cmp_gt_u32_e32 vcc, s91, v35
	s_and_b64 vcc, s[64:65], vcc
	v_sub_u32_e32 v34, v30, v34
	v_cndmask_b32_e32 v55, v219, v56, vcc
	v_cmp_gt_u32_e32 vcc, s91, v34
	s_and_b64 vcc, s[64:65], vcc
	v_lshl_or_b32 v34, s69, 4, v46
	s_cmp_gt_u32 s29, 48
	v_sub_u32_e32 v35, v27, v34
	v_cndmask_b32_e32 v56, v219, v57, vcc
	s_cselect_b64 s[64:65], -1, 0
	v_cmp_gt_u32_e32 vcc, s91, v35
	s_and_b64 vcc, s[64:65], vcc
	v_sub_u32_e32 v35, v34, v27
	v_cndmask_b32_e32 v57, v219, v58, vcc
	v_cmp_lt_u32_e32 vcc, s42, v35
	s_and_b64 vcc, s[64:65], vcc
	v_sub_u32_e32 v35, v28, v34
	v_cndmask_b32_e32 v58, v219, v59, vcc
	v_cmp_gt_u32_e32 vcc, s91, v35
	s_and_b64 vcc, s[64:65], vcc
	v_sub_u32_e32 v34, v30, v34
	v_cndmask_b32_e32 v59, v219, v60, vcc
	v_cmp_gt_u32_e32 vcc, s91, v34
	v_lshl_or_b32 v34, s88, 4, v46
	s_and_b64 vcc, s[64:65], vcc
	v_sub_u32_e32 v35, v27, v34
	v_cndmask_b32_e32 v60, v219, v61, vcc
	v_cmp_gt_u32_e32 vcc, s91, v35
	s_and_b64 vcc, s[10:11], vcc
	v_sub_u32_e32 v35, v34, v27
	v_cndmask_b32_e32 v61, v219, v62, vcc
	v_cmp_lt_u32_e32 vcc, s42, v35
	s_and_b64 vcc, s[10:11], vcc
	v_sub_u32_e32 v35, v28, v34
	v_max3_f32 v25, v25, v29, v22
	v_cndmask_b32_e32 v62, v219, v63, vcc
	v_cmp_gt_u32_e32 vcc, s91, v35
	v_max3_f32 v25, v25, v32, v33
	s_and_b64 vcc, s[10:11], vcc
	v_sub_u32_e32 v34, v30, v34
	v_max3_f32 v25, v25, v40, v31
	v_cndmask_b32_e32 v63, v219, v64, vcc
	v_cmp_gt_u32_e32 vcc, s91, v34
	v_or_b32_e32 v34, s89, v46
	v_max3_f32 v25, v25, v36, v37
	s_and_b64 vcc, s[10:11], vcc
	v_sub_u32_e32 v35, v27, v34
	v_max3_f32 v25, v25, v38, v39
	v_cndmask_b32_e32 v64, v219, v65, vcc
	v_cmp_gt_u32_e32 vcc, s91, v35
	v_sub_u32_e32 v35, v34, v27
	v_max3_f32 v25, v25, v41, v54
	v_cndmask_b32_e32 v65, v219, v74, vcc
	v_cmp_lt_u32_e32 vcc, s42, v35
	v_sub_u32_e32 v35, v28, v34
	v_max3_f32 v25, v25, v55, v56
	v_cndmask_b32_e32 v74, v219, v75, vcc
	v_cmp_gt_u32_e32 vcc, s91, v35
	v_sub_u32_e32 v34, v30, v34
	v_max3_f32 v25, v25, v57, v58
	v_cndmask_b32_e32 v75, v219, v76, vcc
	v_cmp_gt_u32_e32 vcc, s91, v34
	v_or_b32_e32 v34, s49, v46
	v_max3_f32 v25, v25, v59, v60
	v_sub_u32_e32 v35, v27, v34
	v_max3_f32 v25, v25, v61, v62
	v_cndmask_b32_e32 v76, v219, v77, vcc
	v_cmp_gt_u32_e32 vcc, s91, v35
	v_sub_u32_e32 v27, v34, v27
	v_max3_f32 v25, v25, v63, v64
	v_cndmask_b32_e32 v77, v219, v78, vcc
	v_cmp_lt_u32_e32 vcc, s42, v27
	v_sub_u32_e32 v28, v28, v34
	v_max3_f32 v25, v25, v65, v74
	v_cndmask_b32_e32 v27, v219, v79, vcc
	v_cmp_gt_u32_e32 vcc, s91, v28
	v_sub_u32_e32 v28, v30, v34
	v_max3_f32 v25, v25, v75, v76
	v_cndmask_b32_e32 v78, v219, v80, vcc
	v_cmp_gt_u32_e32 vcc, s91, v28
	v_max3_f32 v25, v25, v77, v27
	v_cndmask_b32_e64 v18, v219, v18, s[2:3]
	v_cndmask_b32_e32 v79, v219, v81, vcc
	v_max3_f32 v25, v25, v78, v79
	v_cndmask_b32_e64 v19, v219, v19, s[4:5]
	v_max3_f32 v25, v25, v18, v19
	v_cndmask_b32_e64 v80, v219, v20, s[6:7]
	v_cndmask_b32_e64 v81, v219, v21, s[8:9]
	v_max3_f32 v20, v25, v80, v81
	ds_bpermute_b32 v21, v67, v20
	s_lshl_b32 s29, s59, 5
	s_sub_i32 s29, s29, s26
	s_waitcnt lgkmcnt(0)
; #define LAS __attribute__((address_space(3)))
; __device__ __forceinline__ unsigned cvt_pk_bf16(float lo, float hi) { unsigned r; asm volatile("v_cvt_pk_bf16_f32 %0, %1, %2" : "=v"(r) : "v"(lo), "v"(hi)); return r; }
; __device__ __forceinline__ void phase_attn(Frame& F, const Params& p, int j) {
;     ...
;             m = fmaxf(m, __shfl_xor(m, 16)); m = fmaxf(m, __shfl_xor(m, 32));
;             float l = 0.f; s16x4 pf[9];
; #pragma unroll
;             for (int t = 0; t < 9; ++t) {
;                 float pe[4];
; #pragma unroll
;                 for (int jj = 0; jj < 4; ++jj) { pe[jj] = __expf(s[t][jj] - m); l += pe[jj]; }
;                 u32x2 w; w.x = cvt_pk_bf16(pe[0], pe[1]); w.y = cvt_pk_bf16(pe[2], pe[3]);
;                 pf[t] = __builtin_bit_cast(s16x4, w);
;             }
;             l += __shfl_xor(l, 16); l += __shfl_xor(l, 32);
;             const float rden = 1.0f / (l + __expf(sink - m));
;             f32x4 o[4];
; #pragma unroll
;             for (int dt = 0; dt < 4; ++dt) o[dt] = (f32x4){0.f, 0.f, 0.f, 0.f};
; #pragma unroll
;             for (int t = 0; t < 9; ++t) {
;                 const int kt = ktb + t > 0 ? ktb + t : 0;
; #pragma unroll
;                 for (int dt = 0; dt < 4; ++dt) {
;                     const s16x4 vf = *(const LAS s16x4*)(F.lds + VOFF + (dt * 16 + fr) * VSTR + (kt * 16 - k_lo + fq * 4) * 2);
;                     o[dt] = __builtin_amdgcn_mfma_f32_16x16x16bf16_1k(vf, pf[t], o[dt], 0, 0, 0);
;                 }
;             }
	v_max_f32_e32 v21, v21, v21
	v_max_f32_e32 v20, v20, v21
	ds_bpermute_b32 v21, v68, v20
	s_waitcnt lgkmcnt(0)
	v_max_f32_e32 v21, v21, v21
	v_max_f32_e32 v82, v20, v21
	v_mul_f32_e32 v136, 0xbfb8aa3b, v82
	v_fmamk_f32 v20, v23, 0x3fb8aa3b, v136
	v_exp_f32_e32 v20, v20
	v_fmamk_f32 v23, v24, 0x3fb8aa3b, v136
	v_exp_f32_e32 v23, v23
	v_fmamk_f32 v24, v29, 0x3fb8aa3b, v136
	v_exp_f32_e32 v24, v24
	v_fmamk_f32 v22, v22, 0x3fb8aa3b, v136
	v_exp_f32_e32 v22, v22
	v_add_f32_e32 v21, 0, v20
	v_add_f32_e32 v21, v23, v21
	v_add_f32_e32 v21, v24, v21
	v_cvt_pk_bf16_f32 v34, v20, v23
	v_add_f32_e32 v21, v22, v21
	v_cvt_pk_bf16_f32 v35, v24, v22
	v_fmamk_f32 v20, v32, 0x3fb8aa3b, v136
	v_exp_f32_e32 v20, v20
	v_fmamk_f32 v22, v33, 0x3fb8aa3b, v136
	v_exp_f32_e32 v22, v22
	v_fmamk_f32 v23, v40, 0x3fb8aa3b, v136
	v_exp_f32_e32 v23, v23
	v_fmamk_f32 v24, v31, 0x3fb8aa3b, v136
	v_exp_f32_e32 v24, v24
	v_add_f32_e32 v21, v20, v21
	v_cvt_pk_bf16_f32 v32, v20, v22
	v_add_f32_e32 v21, v22, v21
	v_fmamk_f32 v20, v36, 0x3fb8aa3b, v136
	v_add_f32_e32 v21, v23, v21
	v_cvt_pk_bf16_f32 v33, v23, v24
	v_exp_f32_e32 v20, v20
	v_fmamk_f32 v22, v37, 0x3fb8aa3b, v136
	v_add_f32_e32 v21, v24, v21
	v_exp_f32_e32 v22, v22
	v_fmamk_f32 v23, v38, 0x3fb8aa3b, v136
	v_exp_f32_e32 v23, v23
	v_fmamk_f32 v24, v39, 0x3fb8aa3b, v136
	v_exp_f32_e32 v24, v24
	v_add_f32_e32 v21, v20, v21
	v_cvt_pk_bf16_f32 v36, v20, v22
	v_add_f32_e32 v21, v22, v21
	v_fmamk_f32 v20, v41, 0x3fb8aa3b, v136
	v_add_f32_e32 v21, v23, v21
	v_cvt_pk_bf16_f32 v37, v23, v24
	v_exp_f32_e32 v20, v20
	v_fmamk_f32 v22, v54, 0x3fb8aa3b, v136
	v_add_f32_e32 v21, v24, v21
	v_exp_f32_e32 v22, v22
	v_fmamk_f32 v23, v55, 0x3fb8aa3b, v136
	v_exp_f32_e32 v23, v23
	v_fmamk_f32 v24, v56, 0x3fb8aa3b, v136
	v_exp_f32_e32 v24, v24
	v_add_f32_e32 v21, v20, v21
	v_cvt_pk_bf16_f32 v30, v20, v22
	v_add_f32_e32 v21, v22, v21
	v_fmamk_f32 v20, v57, 0x3fb8aa3b, v136
	v_add_f32_e32 v21, v23, v21
	v_cvt_pk_bf16_f32 v31, v23, v24
	v_exp_f32_e32 v20, v20
	v_fmamk_f32 v22, v58, 0x3fb8aa3b, v136
	v_add_f32_e32 v21, v24, v21
	v_exp_f32_e32 v22, v22
	v_fmamk_f32 v23, v59, 0x3fb8aa3b, v136
	v_exp_f32_e32 v23, v23
	v_fmamk_f32 v24, v60, 0x3fb8aa3b, v136
	v_exp_f32_e32 v24, v24
	v_add_f32_e32 v21, v20, v21
	v_cvt_pk_bf16_f32 v28, v20, v22
	v_add_f32_e32 v21, v22, v21
	v_fmamk_f32 v20, v61, 0x3fb8aa3b, v136
	v_add_f32_e32 v21, v23, v21
	v_cvt_pk_bf16_f32 v29, v23, v24
	v_exp_f32_e32 v20, v20
	v_fmamk_f32 v22, v62, 0x3fb8aa3b, v136
	v_add_f32_e32 v21, v24, v21
	v_exp_f32_e32 v22, v22
	v_fmamk_f32 v23, v63, 0x3fb8aa3b, v136
	v_exp_f32_e32 v23, v23
	v_fmamk_f32 v24, v64, 0x3fb8aa3b, v136
	v_exp_f32_e32 v25, v24
	v_add_f32_e32 v21, v20, v21
	v_add_f32_e32 v21, v22, v21
	v_cvt_pk_bf16_f32 v24, v20, v22
	v_add_f32_e32 v21, v23, v21
	v_fmamk_f32 v20, v65, 0x3fb8aa3b, v136
	v_add_f32_e32 v21, v25, v21
	v_cvt_pk_bf16_f32 v25, v23, v25
	v_exp_f32_e32 v20, v20
	v_fmamk_f32 v22, v74, 0x3fb8aa3b, v136
	v_exp_f32_e32 v22, v22
	v_fmamk_f32 v23, v75, 0x3fb8aa3b, v136
	v_exp_f32_e32 v23, v23
	v_fmamk_f32 v38, v76, 0x3fb8aa3b, v136
	v_exp_f32_e32 v38, v38
	v_add_f32_e32 v21, v20, v21
	v_add_f32_e32 v21, v22, v21
	v_cvt_pk_bf16_f32 v22, v20, v22
	v_add_f32_e32 v21, v23, v21
	v_fmamk_f32 v20, v77, 0x3fb8aa3b, v136
	v_add_f32_e32 v21, v38, v21
	v_cvt_pk_bf16_f32 v23, v23, v38
	v_exp_f32_e32 v20, v20
	v_fmamk_f32 v27, v27, 0x3fb8aa3b, v136
	v_exp_f32_e32 v27, v27
	v_fmamk_f32 v38, v78, 0x3fb8aa3b, v136
	v_exp_f32_e32 v38, v38
	v_fmamk_f32 v39, v79, 0x3fb8aa3b, v136
	v_exp_f32_e32 v39, v39
	v_add_f32_e32 v21, v20, v21
	v_add_f32_e32 v21, v27, v21
	v_add_f32_e32 v21, v38, v21
	v_fmamk_f32 v18, v18, 0x3fb8aa3b, v136
	v_add_f32_e32 v40, v39, v21
	v_cvt_pk_bf16_f32 v20, v20, v27
	v_cvt_pk_bf16_f32 v21, v38, v39
	v_exp_f32_e32 v18, v18
	v_fmamk_f32 v19, v19, 0x3fb8aa3b, v136
	v_exp_f32_e32 v19, v19
	v_fmamk_f32 v38, v80, 0x3fb8aa3b, v136
	v_exp_f32_e32 v38, v38
	v_fmamk_f32 v39, v81, 0x3fb8aa3b, v136
	v_exp_f32_e32 v39, v39
	v_add_f32_e32 v27, v18, v40
	v_add_f32_e32 v27, v19, v27
	v_add_f32_e32 v27, v38, v27
	v_add_f32_e32 v27, v39, v27
	v_cvt_pk_bf16_f32 v18, v18, v19
	v_cvt_pk_bf16_f32 v19, v38, v39
	ds_bpermute_b32 v38, v67, v27
	v_add_u32_e32 v62, s29, v70
	ds_read_b64 v[54:55], v62 offset:36352
	ds_read_b64 v[58:59], v62 offset:42752
	s_lshl_b32 s29, s39, 5
	s_waitcnt lgkmcnt(2)
	v_add_f32_e32 v27, v27, v38
	ds_bpermute_b32 v38, v68, v27
	s_sub_i32 s29, s29, s26
	v_add_u32_e32 v74, s29, v70
	s_waitcnt lgkmcnt(2)
	v_mfma_f32_16x16x16_bf16 v[54:57], v[54:55], v[34:35], 0
	s_waitcnt lgkmcnt(0)
	v_add_f32_e32 v27, v27, v38
	v_fmamk_f32 v38, v73, 0x3fb8aa3b, v136
	v_exp_f32_e32 v38, v38
	v_mfma_f32_16x16x16_bf16 v[58:61], v[58:59], v[34:35], 0
	s_lshl_b32 s29, s38, 5
	s_sub_i32 s29, s29, s26
	v_add_f32_e32 v27, v38, v27
	ds_read_b64 v[38:39], v62 offset:29952
	ds_read_b64 v[62:63], v62 offset:49152
	s_waitcnt lgkmcnt(1)
	v_mfma_f32_16x16x16_bf16 v[38:41], v[38:39], v[34:35], 0
	s_waitcnt lgkmcnt(0)
	v_mfma_f32_16x16x16_bf16 v[62:65], v[62:63], v[34:35], 0
	ds_read_b64 v[34:35], v74 offset:29952
	s_waitcnt lgkmcnt(0)
	v_mfma_f32_16x16x16_bf16 v[38:41], v[34:35], v[32:33], v[38:41]
	ds_read_b64 v[34:35], v74 offset:36352
	s_waitcnt lgkmcnt(0)
	v_mfma_f32_16x16x16_bf16 v[54:57], v[34:35], v[32:33], v[54:57]
	ds_read_b64 v[34:35], v74 offset:42752
	s_waitcnt lgkmcnt(0)
	v_mfma_f32_16x16x16_bf16 v[58:61], v[34:35], v[32:33], v[58:61]
	ds_read_b64 v[34:35], v74 offset:49152
	s_waitcnt lgkmcnt(0)
	v_mfma_f32_16x16x16_bf16 v[32:35], v[34:35], v[32:33], v[62:65]
	s_nop 2
	v_add_u32_e32 v64, s29, v70
	ds_read_b64 v[62:63], v64 offset:29952
	s_lshl_b32 s29, s37, 5
	s_waitcnt lgkmcnt(0)
; #define LAS __attribute__((address_space(3)))
; __device__ __forceinline__ unsigned cvt_pk_bf16(float lo, float hi) { unsigned r; asm volatile("v_cvt_pk_bf16_f32 %0, %1, %2" : "=v"(r) : "v"(lo), "v"(hi)); return r; }
; __device__ __forceinline__ void phase_attn(Frame& F, const Params& p, int j) {
;     ...
; #pragma unroll
;             for (int t = 0; t < 9; ++t) {
;                 const int kt = ktb + t > 0 ? ktb + t : 0;
;                 const LAS unsigned char* kp = F.lds + (kt * 16 - k_lo + fr) * KSTR + fq * 16;
;                 const bf16x8 kf0 = *(const LAS bf16x8*)kp, kf1 = *(const LAS bf16x8*)(kp + 64);
;     ...
; #pragma unroll
;             for (int t = 0; t < 9; ++t) {
;                 const int kt = ktb + t > 0 ? ktb + t : 0;
; #pragma unroll
;                 for (int dt = 0; dt < 4; ++dt) {
;                     const s16x4 vf = *(const LAS s16x4*)(F.lds + VOFF + (dt * 16 + fr) * VSTR + (kt * 16 - k_lo + fq * 4) * 2);
;                     o[dt] = __builtin_amdgcn_mfma_f32_16x16x16bf16_1k(vf, pf[t], o[dt], 0, 0, 0);
;                 }
;             }
;             bf16_t* op = F.OB + (size_t)qrow * D + h * 64 + fq * 4;
; #pragma unroll
;             for (int dt = 0; dt < 4; ++dt) { u32x2 w; w.x = cvt_pk_bf16(o[dt][0] * rden, o[dt][1] * rden); w.y = cvt_pk_bf16(o[dt][2] * rden, o[dt][3] * rden); *(u32x2*)(op + dt * 16) = w; }
	v_mfma_f32_16x16x16_bf16 v[38:41], v[62:63], v[36:37], v[38:41]
	ds_read_b64 v[62:63], v64 offset:36352
	s_sub_i32 s29, s29, s26
	s_waitcnt lgkmcnt(0)
	v_mfma_f32_16x16x16_bf16 v[54:57], v[62:63], v[36:37], v[54:57]
	ds_read_b64 v[62:63], v64 offset:42752
	s_waitcnt lgkmcnt(0)
	v_mfma_f32_16x16x16_bf16 v[58:61], v[62:63], v[36:37], v[58:61]
	ds_read_b64 v[62:63], v64 offset:49152
	s_waitcnt lgkmcnt(0)
	v_mfma_f32_16x16x16_bf16 v[32:35], v[62:63], v[36:37], v[32:35]
	v_add_u32_e32 v62, s29, v70
	ds_read_b64 v[36:37], v62 offset:29952
	s_lshl_b32 s29, s36, 5
	s_waitcnt lgkmcnt(0)
	v_mfma_f32_16x16x16_bf16 v[36:39], v[36:37], v[30:31], v[38:41]
	s_nop 2
	ds_read_b64 v[40:41], v62 offset:36352
	s_sub_i32 s29, s29, s26
	s_waitcnt lgkmcnt(0)
	v_mfma_f32_16x16x16_bf16 v[54:57], v[40:41], v[30:31], v[54:57]
	ds_read_b64 v[40:41], v62 offset:42752
	s_waitcnt lgkmcnt(0)
	v_mfma_f32_16x16x16_bf16 v[58:61], v[40:41], v[30:31], v[58:61]
	ds_read_b64 v[40:41], v62 offset:49152
	v_add_u32_e32 v62, s29, v70
	s_lshl_b32 s29, s35, 5
	s_waitcnt lgkmcnt(0)
	v_mfma_f32_16x16x16_bf16 v[30:33], v[40:41], v[30:31], v[32:35]
	s_nop 2
	ds_read_b64 v[34:35], v62 offset:29952
	s_sub_i32 s29, s29, s26
	s_waitcnt lgkmcnt(0)
	v_mfma_f32_16x16x16_bf16 v[34:37], v[34:35], v[28:29], v[36:39]
	s_nop 2
	ds_read_b64 v[38:39], v62 offset:36352
	s_waitcnt lgkmcnt(0)
	v_mfma_f32_16x16x16_bf16 v[38:41], v[38:39], v[28:29], v[54:57]
	s_nop 2
	ds_read_b64 v[54:55], v62 offset:42752
	s_waitcnt lgkmcnt(0)
	v_mfma_f32_16x16x16_bf16 v[54:57], v[54:55], v[28:29], v[58:61]
	s_nop 2
	ds_read_b64 v[58:59], v62 offset:49152
	s_waitcnt lgkmcnt(0)
	v_mfma_f32_16x16x16_bf16 v[28:31], v[58:59], v[28:29], v[30:33]
	v_add_u32_e32 v58, s29, v70
	s_nop 1
	ds_read_b64 v[32:33], v58 offset:29952
	s_lshl_b32 s29, s34, 5
	s_waitcnt lgkmcnt(0)
	v_mfma_f32_16x16x16_bf16 v[32:35], v[32:33], v[24:25], v[34:37]
	s_nop 2
	ds_read_b64 v[36:37], v58 offset:36352
	s_sub_i32 s29, s29, s26
	s_waitcnt lgkmcnt(0)
	v_mfma_f32_16x16x16_bf16 v[36:39], v[36:37], v[24:25], v[38:41]
	s_nop 2
	ds_read_b64 v[40:41], v58 offset:42752
	s_waitcnt lgkmcnt(0)
	v_mfma_f32_16x16x16_bf16 v[54:57], v[40:41], v[24:25], v[54:57]
	ds_read_b64 v[40:41], v58 offset:49152
	s_waitcnt lgkmcnt(0)
	v_mfma_f32_16x16x16_bf16 v[28:31], v[40:41], v[24:25], v[28:31]
	v_add_u32_e32 v40, s29, v70
	ds_read_b64 v[24:25], v40 offset:29952
	s_lshl_b32 s29, s31, 5
	s_waitcnt lgkmcnt(0)
	v_mfma_f32_16x16x16_bf16 v[32:35], v[24:25], v[22:23], v[32:35]
	ds_read_b64 v[24:25], v40 offset:36352
	s_sub_i32 s29, s29, s26
	s_waitcnt lgkmcnt(0)
	v_mfma_f32_16x16x16_bf16 v[36:39], v[24:25], v[22:23], v[36:39]
	ds_read_b64 v[24:25], v40 offset:42752
	s_waitcnt lgkmcnt(0)
	v_mfma_f32_16x16x16_bf16 v[54:57], v[24:25], v[22:23], v[54:57]
	ds_read_b64 v[24:25], v40 offset:49152
	v_add_u32_e32 v40, s29, v70
	s_lshr_b32 s29, s28, 4
	s_waitcnt lgkmcnt(0)
	v_mfma_f32_16x16x16_bf16 v[22:25], v[24:25], v[22:23], v[28:31]
	s_nop 2
	ds_read_b64 v[28:29], v40 offset:29952
	s_add_i32 s39, s29, -8
	s_max_i32 s38, s39, 0
	s_waitcnt lgkmcnt(0)
	v_mfma_f32_16x16x16_bf16 v[28:31], v[28:29], v[20:21], v[32:35]
	s_nop 2
	ds_read_b64 v[32:33], v40 offset:36352
	s_add_i32 s49, s29, -7
	s_max_i32 s37, s49, 0
	s_waitcnt lgkmcnt(0)
	v_mfma_f32_16x16x16_bf16 v[32:35], v[32:33], v[20:21], v[36:39]
	s_nop 2
	ds_read_b64 v[36:37], v40 offset:42752
	ds_read_b64 v[40:41], v40 offset:49152
	s_add_i32 s59, s29, -6
	s_waitcnt lgkmcnt(1)
	v_mfma_f32_16x16x16_bf16 v[36:39], v[36:37], v[20:21], v[54:57]
	s_max_i32 s36, s59, 0
	s_add_i32 s64, s29, -5
	s_max_i32 s35, s64, 0
	s_waitcnt lgkmcnt(0)
	v_mfma_f32_16x16x16_bf16 v[20:23], v[40:41], v[20:21], v[22:25]
	v_lshl_add_u32 v40, s30, 1, v70
	s_add_i32 s65, s29, -4
	s_max_i32 s34, s65, 0
	ds_read_b64 v[24:25], v40 offset:29952
	s_waitcnt lgkmcnt(0)
	v_mfma_f32_16x16x16_bf16 v[28:31], v[24:25], v[18:19], v[28:31]
	ds_read_b64 v[24:25], v40 offset:36352
	s_waitcnt lgkmcnt(0)
	v_mfma_f32_16x16x16_bf16 v[32:35], v[24:25], v[18:19], v[32:35]
	ds_read_b64 v[24:25], v40 offset:42752
	s_waitcnt lgkmcnt(0)
	v_mfma_f32_16x16x16_bf16 v[36:39], v[24:25], v[18:19], v[36:39]
	ds_read_b64 v[24:25], v40 offset:49152
	s_waitcnt lgkmcnt(0)
	v_mfma_f32_16x16x16_bf16 v[18:21], v[24:25], v[18:19], v[20:23]
	s_nop 2
	v_div_scale_f32 v22, s[30:31], v27, v27, 1.0
	v_rcp_f32_e32 v23, v22
	s_lshl_b32 s30, s38, 4
	s_sub_i32 s30, s30, s27
	v_fma_f32 v24, -v22, v23, 1.0
	v_fmac_f32_e32 v23, v24, v23
	v_div_scale_f32 v24, vcc, 1.0, v27, 1.0
	v_mul_f32_e32 v25, v24, v23
	v_fma_f32 v40, -v22, v25, v24
	v_fmac_f32_e32 v25, v40, v23
	v_fma_f32 v22, -v22, v25, v24
	v_div_fmas_f32 v22, v22, v23, v25
	v_div_fixup_f32 v40, v22, v27, 1.0
	v_ashrrev_i32_e32 v27, 31, v26
	v_lshlrev_b64 v[22:23], 12, v[26:27]
	v_lshl_add_u64 v[22:23], s[86:87], 0, v[22:23]
	v_mul_f32_e32 v24, v40, v28
	v_mul_f32_e32 v25, v40, v29
	v_lshl_add_u64 v[22:23], v[22:23], 0, s[82:83]
	v_cvt_pk_bf16_f32 v24, v24, v25
	v_mul_f32_e32 v25, v40, v30
	v_lshl_add_u64 v[22:23], v[22:23], 0, v[168:169]
	v_mul_f32_e32 v26, v40, v31
	v_cvt_pk_bf16_f32 v25, v25, v26
	global_store_dwordx2 v[22:23], v[24:25], off
	v_mul_f32_e32 v24, v40, v32
	v_mul_f32_e32 v25, v40, v33
	v_cvt_pk_bf16_f32 v24, v24, v25
	v_mul_f32_e32 v25, v40, v34
	v_mul_f32_e32 v26, v40, v35
	v_cvt_pk_bf16_f32 v25, v25, v26
	global_store_dwordx2 v[22:23], v[24:25], off offset:32
	v_mul_f32_e32 v24, v40, v36
	v_mul_f32_e32 v25, v40, v37
	v_cvt_pk_bf16_f32 v24, v24, v25
	v_mul_f32_e32 v25, v40, v38
	v_mul_f32_e32 v18, v40, v18
	v_mul_f32_e32 v19, v40, v19
	v_mul_f32_e32 v26, v40, v39
	v_cvt_pk_bf16_f32 v25, v25, v26
	global_store_dwordx2 v[22:23], v[24:25], off offset:64
	v_cvt_pk_bf16_f32 v18, v18, v19
	v_mul_f32_e32 v19, v40, v20
	v_mul_f32_e32 v20, v40, v21
	v_cvt_pk_bf16_f32 v19, v19, v20
	v_or_b32_e32 v20, s30, v126
	global_store_dwordx2 v[22:23], v[18:19], off offset:96
	v_mad_u64_u32 v[24:25], s[30:31], v20, s80, v[48:49]
	ds_read_b128 v[20:23], v24
	ds_read_b128 v[24:27], v24 offset:64
	s_waitcnt vmcnt(15) lgkmcnt(1)
; #define LAS __attribute__((address_space(3)))
; __device__ __forceinline__ void phase_attn(Frame& F, const Params& p, int j) {
;     ...
; #pragma unroll
;             for (int t = 0; t < 9; ++t) {
;                 const int kt = ktb + t > 0 ? ktb + t : 0;
;                 const LAS unsigned char* kp = F.lds + (kt * 16 - k_lo + fr) * KSTR + fq * 16;
;                 const bf16x8 kf0 = *(const LAS bf16x8*)kp, kf1 = *(const LAS bf16x8*)(kp + 64);
;                 s[t] = (f32x4){0.f, 0.f, 0.f, 0.f};
;                 s[t] = __builtin_amdgcn_mfma_f32_16x16x32_bf16(kf0, qf0, s[t], 0, 0, 0);
;                 s[t] = __builtin_amdgcn_mfma_f32_16x16x32_bf16(kf1, qf1, s[t], 0, 0, 0);
;             }
;             float m = sink;
; #pragma unroll
;             for (int t = 0; t < 9; ++t)
; #pragma unroll
;                 for (int jj = 0; jj < 4; ++jj) { const int key = (ktb + t) * 16 + fq * 4 + jj, dd = q - key; const bool ok = key >= 0 && dd >= 0 && dd < 128;
;                     s[t][jj] = ok ? s[t][jj] : -1e30f; m = fmaxf(m, s[t][jj]); }
	v_mfma_f32_16x16x32_bf16 v[20:23], v[20:23], v[14:17], 0
	s_lshl_b32 s30, s37, 4
	s_sub_i32 s30, s30, s27
	v_or_b32_e32 v19, s28, v126
	s_waitcnt vmcnt(14) lgkmcnt(0)
	v_mfma_f32_16x16x32_bf16 v[20:23], v[24:27], v[10:13], v[20:23]
	v_or_b32_e32 v24, s30, v126
	v_mad_u64_u32 v[28:29], s[30:31], v24, s80, v[48:49]
	ds_read_b128 v[24:27], v28
	ds_read_b128 v[28:31], v28 offset:64
	s_waitcnt lgkmcnt(1)
	v_mfma_f32_16x16x32_bf16 v[24:27], v[24:27], v[14:17], 0
	s_lshl_b32 s30, s36, 4
	s_sub_i32 s30, s30, s27
	s_sub_i32 s28, s28, s27
	s_waitcnt lgkmcnt(0)
	v_mfma_f32_16x16x32_bf16 v[24:27], v[28:31], v[10:13], v[24:27]
	v_or_b32_e32 v28, s30, v126
	v_mad_u64_u32 v[32:33], s[30:31], v28, s80, v[48:49]
	ds_read_b128 v[28:31], v32
	ds_read_b128 v[32:35], v32 offset:64
	s_waitcnt lgkmcnt(1)
	v_mfma_f32_16x16x32_bf16 v[28:31], v[28:31], v[14:17], 0
	s_lshl_b32 s30, s35, 4
	s_sub_i32 s30, s30, s27
	v_add_u32_e32 v18, s25, v19
	s_waitcnt lgkmcnt(0)
	v_mfma_f32_16x16x32_bf16 v[28:31], v[32:35], v[10:13], v[28:31]
	v_or_b32_e32 v32, s30, v126
	v_mad_u64_u32 v[36:37], s[30:31], v32, s80, v[48:49]
	ds_read_b128 v[32:35], v36
	ds_read_b128 v[36:39], v36 offset:64
	s_waitcnt lgkmcnt(1)
	v_mfma_f32_16x16x32_bf16 v[32:35], v[32:35], v[14:17], 0
	s_lshl_b32 s30, s34, 4
	s_sub_i32 s30, s30, s27
	s_waitcnt lgkmcnt(0)
	v_mfma_f32_16x16x32_bf16 v[32:35], v[36:39], v[10:13], v[32:35]
	v_or_b32_e32 v36, s30, v126
	v_mad_u64_u32 v[40:41], s[30:31], v36, s80, v[48:49]
	ds_read_b128 v[36:39], v40
	ds_read_b128 v[54:57], v40 offset:64
	s_add_i32 s31, s29, -3
	s_waitcnt lgkmcnt(1)
	v_mfma_f32_16x16x32_bf16 v[36:39], v[36:39], v[14:17], 0
	s_lshl_b32 s66, s31, 4
	s_sub_i32 s30, s66, s27
	v_or_b32_e32 v40, s30, v126
	v_mad_i32_i24 v40, v40, s80, v48
	s_waitcnt lgkmcnt(0)
	v_mfma_f32_16x16x32_bf16 v[36:39], v[54:57], v[10:13], v[36:39]
	ds_read_b128 v[54:57], v40
	ds_read_b128 v[58:61], v40 offset:64
	s_add_i32 s30, s29, -2
	s_lshl_b32 s67, s30, 4
	s_waitcnt lgkmcnt(1)
	v_mfma_f32_16x16x32_bf16 v[54:57], v[54:57], v[14:17], 0
	s_sub_i32 s68, s67, s27
	v_or_b32_e32 v40, s68, v126
	v_mad_i32_i24 v40, v40, s80, v48
	s_waitcnt lgkmcnt(0)
	v_mfma_f32_16x16x32_bf16 v[54:57], v[58:61], v[10:13], v[54:57]
	ds_read_b128 v[58:61], v40
	ds_read_b128 v[62:65], v40 offset:64
	s_add_i32 s29, s29, -1
	s_lshl_b32 s68, s29, 4
	s_waitcnt lgkmcnt(1)
	v_mfma_f32_16x16x32_bf16 v[58:61], v[58:61], v[14:17], 0
	s_sub_i32 s69, s68, s27
	v_or_b32_e32 v40, s69, v126
	v_mad_i32_i24 v40, v40, s80, v48
	s_waitcnt lgkmcnt(0)
	v_mfma_f32_16x16x32_bf16 v[58:61], v[62:65], v[10:13], v[58:61]
	ds_read_b128 v[62:65], v40
	ds_read_b128 v[74:77], v40 offset:64
	v_or_b32_e32 v40, s28, v126
	v_mad_i32_i24 v40, v40, s80, v48
	s_waitcnt lgkmcnt(1)
	v_mfma_f32_16x16x32_bf16 v[62:65], v[62:65], v[14:17], 0
	s_waitcnt lgkmcnt(0)
	v_mfma_f32_16x16x32_bf16 v[62:65], v[74:77], v[10:13], v[62:65]
	ds_read_b128 v[74:77], v40
	ds_read_b128 v[78:81], v40 offset:64
	s_waitcnt lgkmcnt(1)
	v_mfma_f32_16x16x32_bf16 v[14:17], v[74:77], v[14:17], 0
	s_waitcnt lgkmcnt(0)
	v_mfma_f32_16x16x32_bf16 v[10:13], v[78:81], v[10:13], v[14:17]
	s_nop 5
	v_lshl_or_b32 v14, s39, 4, v46
	v_sub_u32_e32 v15, v19, v14
	v_cmp_gt_u32_e32 vcc, s91, v15
	s_and_b64 vcc, s[14:15], vcc
	v_sub_u32_e32 v16, v14, v19
	v_cndmask_b32_e32 v15, v219, v20, vcc
	v_cmp_lt_u32_e32 vcc, s42, v16
	s_and_b64 vcc, s[14:15], vcc
	v_add_u32_e32 v20, -2, v19
	v_cndmask_b32_e32 v16, v219, v21, vcc
	v_sub_u32_e32 v21, v20, v14
	v_cmp_gt_u32_e32 vcc, s91, v21
	s_and_b64 vcc, s[14:15], vcc
	v_max3_f32 v17, v73, v15, v16
	v_cndmask_b32_e32 v21, v219, v22, vcc
	v_add_u32_e32 v22, -3, v19
	v_sub_u32_e32 v14, v22, v14
	v_cmp_gt_u32_e32 vcc, s91, v14
	s_and_b64 vcc, s[14:15], vcc
	v_cndmask_b32_e64 v10, v219, v10, s[2:3]
	v_cndmask_b32_e32 v14, v219, v23, vcc
	v_lshl_or_b32 v23, s49, 4, v46
	v_sub_u32_e32 v40, v19, v23
	v_cmp_gt_u32_e32 vcc, s91, v40
	s_and_b64 vcc, s[16:17], vcc
	v_sub_u32_e32 v40, v23, v19
	v_cndmask_b32_e32 v24, v219, v24, vcc
	v_cmp_lt_u32_e32 vcc, s42, v40
	s_and_b64 vcc, s[16:17], vcc
	v_sub_u32_e32 v40, v20, v23
	v_cndmask_b32_e32 v25, v219, v25, vcc
	v_cmp_gt_u32_e32 vcc, s91, v40
	s_and_b64 vcc, s[16:17], vcc
	v_sub_u32_e32 v23, v22, v23
	v_cndmask_b32_e32 v40, v219, v26, vcc
	v_cmp_gt_u32_e32 vcc, s91, v23
	s_and_b64 vcc, s[16:17], vcc
	v_lshl_or_b32 v26, s59, 4, v46
	v_cndmask_b32_e32 v23, v219, v27, vcc
	v_sub_u32_e32 v27, v19, v26
	v_cmp_gt_u32_e32 vcc, s91, v27
	s_and_b64 vcc, s[18:19], vcc
	v_sub_u32_e32 v27, v26, v19
	v_cndmask_b32_e32 v28, v219, v28, vcc
	v_cmp_lt_u32_e32 vcc, s42, v27
	s_and_b64 vcc, s[18:19], vcc
	v_sub_u32_e32 v27, v20, v26
	v_cndmask_b32_e32 v29, v219, v29, vcc
	v_cmp_gt_u32_e32 vcc, s91, v27
	s_and_b64 vcc, s[18:19], vcc
	v_sub_u32_e32 v26, v22, v26
	v_cndmask_b32_e32 v30, v219, v30, vcc
	v_cmp_gt_u32_e32 vcc, s91, v26
	v_lshl_or_b32 v26, s64, 4, v46
	s_and_b64 vcc, s[18:19], vcc
	v_sub_u32_e32 v27, v19, v26
	v_cndmask_b32_e32 v31, v219, v31, vcc
	v_cmp_gt_u32_e32 vcc, s91, v27
	s_and_b64 vcc, s[20:21], vcc
	v_sub_u32_e32 v27, v26, v19
	v_cndmask_b32_e32 v32, v219, v32, vcc
	v_cmp_lt_u32_e32 vcc, s42, v27
	s_and_b64 vcc, s[20:21], vcc
	v_sub_u32_e32 v27, v20, v26
	v_cndmask_b32_e32 v33, v219, v33, vcc
	v_cmp_gt_u32_e32 vcc, s91, v27
	s_and_b64 vcc, s[20:21], vcc
	v_sub_u32_e32 v26, v22, v26
	v_cndmask_b32_e32 v34, v219, v34, vcc
	v_cmp_gt_u32_e32 vcc, s91, v26
	v_lshl_or_b32 v26, s65, 4, v46
	s_and_b64 vcc, s[20:21], vcc
	v_sub_u32_e32 v27, v19, v26
	v_cndmask_b32_e32 v35, v219, v35, vcc
	v_cmp_gt_u32_e32 vcc, s91, v27
	s_and_b64 vcc, s[10:11], vcc
	v_sub_u32_e32 v27, v26, v19
	v_cndmask_b32_e32 v36, v219, v36, vcc
; __device__ __forceinline__ unsigned cvt_pk_bf16(float lo, float hi) { unsigned r; asm volatile("v_cvt_pk_bf16_f32 %0, %1, %2" : "=v"(r) : "v"(lo), "v"(hi)); return r; }
; __device__ __forceinline__ void phase_attn(Frame& F, const Params& p, int j) {
;     ...
;             float m = sink;
; #pragma unroll
;             for (int t = 0; t < 9; ++t)
; #pragma unroll
;                 for (int jj = 0; jj < 4; ++jj) { const int key = (ktb + t) * 16 + fq * 4 + jj, dd = q - key; const bool ok = key >= 0 && dd >= 0 && dd < 128;
;                     s[t][jj] = ok ? s[t][jj] : -1e30f; m = fmaxf(m, s[t][jj]); }
;             m = fmaxf(m, __shfl_xor(m, 16)); m = fmaxf(m, __shfl_xor(m, 32));
;             float l = 0.f; s16x4 pf[9];
; #pragma unroll
;             for (int t = 0; t < 9; ++t) {
;                 float pe[4];
; #pragma unroll
;                 for (int jj = 0; jj < 4; ++jj) { pe[jj] = __expf(s[t][jj] - m); l += pe[jj]; }
;                 u32x2 w; w.x = cvt_pk_bf16(pe[0], pe[1]); w.y = cvt_pk_bf16(pe[2], pe[3]);
;                 pf[t] = __builtin_bit_cast(s16x4, w);
;             }
;             l += __shfl_xor(l, 16); l += __shfl_xor(l, 32);
;             const float rden = 1.0f / (l + __expf(sink - m));
	v_cmp_lt_u32_e32 vcc, s42, v27
	s_and_b64 vcc, s[10:11], vcc
	v_sub_u32_e32 v27, v20, v26
	v_cndmask_b32_e32 v37, v219, v37, vcc
	v_cmp_gt_u32_e32 vcc, s91, v27
	s_and_b64 vcc, s[10:11], vcc
	v_sub_u32_e32 v26, v22, v26
	v_cndmask_b32_e32 v38, v219, v38, vcc
	v_cmp_gt_u32_e32 vcc, s91, v26
	v_or_b32_e32 v26, s66, v46
	s_and_b64 vcc, s[10:11], vcc
	v_sub_u32_e32 v27, v19, v26
	v_cndmask_b32_e32 v39, v219, v39, vcc
	v_cmp_gt_u32_e32 vcc, s91, v27
	v_sub_u32_e32 v27, v26, v19
	v_max3_f32 v17, v17, v21, v14
	v_cndmask_b32_e32 v41, v219, v54, vcc
	v_cmp_lt_u32_e32 vcc, s42, v27
	v_sub_u32_e32 v27, v20, v26
	v_max3_f32 v17, v17, v24, v25
	v_cndmask_b32_e32 v54, v219, v55, vcc
	v_cmp_gt_u32_e32 vcc, s91, v27
	v_sub_u32_e32 v26, v22, v26
	v_max3_f32 v17, v17, v40, v23
	v_cndmask_b32_e32 v55, v219, v56, vcc
	v_cmp_gt_u32_e32 vcc, s91, v26
	v_or_b32_e32 v26, s67, v46
	v_max3_f32 v17, v17, v28, v29
	v_sub_u32_e32 v27, v19, v26
	v_max3_f32 v17, v17, v30, v31
	v_cndmask_b32_e32 v56, v219, v57, vcc
	v_cmp_gt_u32_e32 vcc, s91, v27
	v_sub_u32_e32 v27, v26, v19
	v_max3_f32 v17, v17, v32, v33
	v_cndmask_b32_e32 v57, v219, v58, vcc
	v_cmp_lt_u32_e32 vcc, s42, v27
	v_sub_u32_e32 v27, v20, v26
	v_max3_f32 v17, v17, v34, v35
	v_cndmask_b32_e32 v58, v219, v59, vcc
	v_cmp_gt_u32_e32 vcc, s91, v27
	v_sub_u32_e32 v26, v22, v26
	v_max3_f32 v17, v17, v36, v37
	v_cndmask_b32_e32 v59, v219, v60, vcc
	v_cmp_gt_u32_e32 vcc, s91, v26
	v_or_b32_e32 v26, s68, v46
	v_max3_f32 v17, v17, v38, v39
	v_sub_u32_e32 v27, v19, v26
	v_max3_f32 v17, v17, v41, v54
	v_cndmask_b32_e32 v60, v219, v61, vcc
	v_cmp_gt_u32_e32 vcc, s91, v27
	v_sub_u32_e32 v19, v26, v19
	v_max3_f32 v17, v17, v55, v56
	v_cndmask_b32_e32 v61, v219, v62, vcc
	v_cmp_lt_u32_e32 vcc, s42, v19
	v_sub_u32_e32 v20, v20, v26
	v_max3_f32 v17, v17, v57, v58
	v_cndmask_b32_e32 v19, v219, v63, vcc
	v_cmp_gt_u32_e32 vcc, s91, v20
	v_sub_u32_e32 v20, v22, v26
	v_max3_f32 v17, v17, v59, v60
	v_cndmask_b32_e32 v62, v219, v64, vcc
	v_cmp_gt_u32_e32 vcc, s91, v20
	v_max3_f32 v17, v17, v61, v19
	v_cndmask_b32_e64 v11, v219, v11, s[4:5]
	v_cndmask_b32_e32 v63, v219, v65, vcc
	v_max3_f32 v17, v17, v62, v63
	v_max3_f32 v17, v17, v10, v11
	v_cndmask_b32_e64 v64, v219, v12, s[6:7]
	v_cndmask_b32_e64 v65, v219, v13, s[8:9]
	v_max3_f32 v12, v17, v64, v65
	ds_bpermute_b32 v13, v67, v12
	s_lshl_b32 s10, s38, 5
	s_sub_i32 s10, s10, s26
	s_waitcnt lgkmcnt(0)
	v_max_f32_e32 v13, v13, v13
	v_max_f32_e32 v12, v12, v13
	ds_bpermute_b32 v13, v68, v12
	s_waitcnt lgkmcnt(0)
	v_max_f32_e32 v13, v13, v13
	v_max_f32_e32 v74, v12, v13
	v_mul_f32_e32 v136, 0xbfb8aa3b, v74
	v_fmamk_f32 v12, v15, 0x3fb8aa3b, v136
	v_exp_f32_e32 v12, v12
	v_fmamk_f32 v15, v16, 0x3fb8aa3b, v136
	v_exp_f32_e32 v15, v15
	v_fmamk_f32 v16, v21, 0x3fb8aa3b, v136
	v_exp_f32_e32 v16, v16
	v_fmamk_f32 v14, v14, 0x3fb8aa3b, v136
	v_exp_f32_e32 v14, v14
	v_add_f32_e32 v13, 0, v12
	v_add_f32_e32 v13, v15, v13
	v_add_f32_e32 v13, v16, v13
	v_cvt_pk_bf16_f32 v26, v12, v15
	v_add_f32_e32 v13, v14, v13
	v_cvt_pk_bf16_f32 v27, v16, v14
	v_fmamk_f32 v12, v24, 0x3fb8aa3b, v136
	v_exp_f32_e32 v12, v12
	v_fmamk_f32 v14, v25, 0x3fb8aa3b, v136
	v_exp_f32_e32 v14, v14
	v_fmamk_f32 v15, v40, 0x3fb8aa3b, v136
	v_exp_f32_e32 v15, v15
	v_fmamk_f32 v16, v23, 0x3fb8aa3b, v136
	v_exp_f32_e32 v16, v16
	v_add_f32_e32 v13, v12, v13
	v_cvt_pk_bf16_f32 v24, v12, v14
	v_add_f32_e32 v13, v14, v13
	v_fmamk_f32 v12, v28, 0x3fb8aa3b, v136
	v_add_f32_e32 v13, v15, v13
	v_cvt_pk_bf16_f32 v25, v15, v16
	v_exp_f32_e32 v12, v12
	v_fmamk_f32 v14, v29, 0x3fb8aa3b, v136
	v_add_f32_e32 v13, v16, v13
	v_exp_f32_e32 v14, v14
	v_fmamk_f32 v15, v30, 0x3fb8aa3b, v136
	v_exp_f32_e32 v15, v15
	v_fmamk_f32 v16, v31, 0x3fb8aa3b, v136
	v_exp_f32_e32 v16, v16
	v_add_f32_e32 v13, v12, v13
	v_cvt_pk_bf16_f32 v28, v12, v14
	v_add_f32_e32 v13, v14, v13
	v_fmamk_f32 v12, v32, 0x3fb8aa3b, v136
	v_add_f32_e32 v13, v15, v13
	v_cvt_pk_bf16_f32 v29, v15, v16
	v_exp_f32_e32 v12, v12
	v_fmamk_f32 v14, v33, 0x3fb8aa3b, v136
	v_add_f32_e32 v13, v16, v13
	v_exp_f32_e32 v14, v14
	v_fmamk_f32 v15, v34, 0x3fb8aa3b, v136
	v_exp_f32_e32 v15, v15
	v_fmamk_f32 v16, v35, 0x3fb8aa3b, v136
	v_exp_f32_e32 v16, v16
	v_add_f32_e32 v13, v12, v13
	v_cvt_pk_bf16_f32 v22, v12, v14
	v_add_f32_e32 v13, v14, v13
	v_fmamk_f32 v12, v36, 0x3fb8aa3b, v136
	v_add_f32_e32 v13, v15, v13
	v_cvt_pk_bf16_f32 v23, v15, v16
	v_exp_f32_e32 v12, v12
	v_fmamk_f32 v14, v37, 0x3fb8aa3b, v136
	v_add_f32_e32 v13, v16, v13
	v_exp_f32_e32 v14, v14
	v_fmamk_f32 v15, v38, 0x3fb8aa3b, v136
	v_exp_f32_e32 v15, v15
	v_fmamk_f32 v16, v39, 0x3fb8aa3b, v136
	v_exp_f32_e32 v16, v16
	v_add_f32_e32 v13, v12, v13
	v_cvt_pk_bf16_f32 v20, v12, v14
	v_add_f32_e32 v13, v14, v13
	v_fmamk_f32 v12, v41, 0x3fb8aa3b, v136
	v_add_f32_e32 v13, v15, v13
	v_cvt_pk_bf16_f32 v21, v15, v16
	v_exp_f32_e32 v12, v12
	v_fmamk_f32 v14, v54, 0x3fb8aa3b, v136
	v_add_f32_e32 v13, v16, v13
	v_exp_f32_e32 v14, v14
	v_fmamk_f32 v15, v55, 0x3fb8aa3b, v136
	v_exp_f32_e32 v15, v15
	v_fmamk_f32 v16, v56, 0x3fb8aa3b, v136
	v_exp_f32_e32 v17, v16
	v_add_f32_e32 v13, v12, v13
	v_add_f32_e32 v13, v14, v13
	v_cvt_pk_bf16_f32 v16, v12, v14
	v_add_f32_e32 v13, v15, v13
	v_fmamk_f32 v12, v57, 0x3fb8aa3b, v136
	v_add_f32_e32 v13, v17, v13
	v_cvt_pk_bf16_f32 v17, v15, v17
	v_exp_f32_e32 v12, v12
	v_fmamk_f32 v14, v58, 0x3fb8aa3b, v136
	v_exp_f32_e32 v14, v14
	v_fmamk_f32 v15, v59, 0x3fb8aa3b, v136
	v_exp_f32_e32 v15, v15
	v_fmamk_f32 v30, v60, 0x3fb8aa3b, v136
	v_exp_f32_e32 v30, v30
	v_add_f32_e32 v13, v12, v13
	v_add_f32_e32 v13, v14, v13
	v_cvt_pk_bf16_f32 v14, v12, v14
	v_add_f32_e32 v13, v15, v13
	v_fmamk_f32 v12, v61, 0x3fb8aa3b, v136
	v_add_f32_e32 v13, v30, v13
	v_cvt_pk_bf16_f32 v15, v15, v30
	v_exp_f32_e32 v12, v12
	v_fmamk_f32 v19, v19, 0x3fb8aa3b, v136
	v_exp_f32_e32 v19, v19
	v_fmamk_f32 v30, v62, 0x3fb8aa3b, v136
	v_exp_f32_e32 v30, v30
	v_fmamk_f32 v31, v63, 0x3fb8aa3b, v136
	v_exp_f32_e32 v31, v31
	v_add_f32_e32 v13, v12, v13
	v_add_f32_e32 v13, v19, v13
	v_add_f32_e32 v13, v30, v13
	v_fmamk_f32 v10, v10, 0x3fb8aa3b, v136
	v_add_f32_e32 v32, v31, v13
	v_cvt_pk_bf16_f32 v12, v12, v19
	v_cvt_pk_bf16_f32 v13, v30, v31
	v_exp_f32_e32 v10, v10
	v_fmamk_f32 v11, v11, 0x3fb8aa3b, v136
	v_exp_f32_e32 v11, v11
	v_fmamk_f32 v30, v64, 0x3fb8aa3b, v136
	v_exp_f32_e32 v30, v30
	v_fmamk_f32 v31, v65, 0x3fb8aa3b, v136
	v_exp_f32_e32 v31, v31
	v_add_f32_e32 v19, v10, v32
	v_add_f32_e32 v19, v11, v19
	v_add_f32_e32 v19, v30, v19
	v_add_f32_e32 v19, v31, v19
	v_cvt_pk_bf16_f32 v10, v10, v11
	v_cvt_pk_bf16_f32 v11, v30, v31
	ds_bpermute_b32 v30, v67, v19
	v_add_u32_e32 v54, s10, v70
	ds_read_b64 v[34:35], v54 offset:36352
	ds_read_b64 v[38:39], v54 offset:42752
	s_lshl_b32 s10, s37, 5
	s_waitcnt lgkmcnt(2)
; #define LAS __attribute__((address_space(3)))
; __device__ __forceinline__ unsigned cvt_pk_bf16(float lo, float hi) { unsigned r; asm volatile("v_cvt_pk_bf16_f32 %0, %1, %2" : "=v"(r) : "v"(lo), "v"(hi)); return r; }
; __device__ __forceinline__ void phase_attn(Frame& F, const Params& p, int j) {
;     ...
;             l += __shfl_xor(l, 16); l += __shfl_xor(l, 32);
;             const float rden = 1.0f / (l + __expf(sink - m));
;             f32x4 o[4];
; #pragma unroll
;             for (int dt = 0; dt < 4; ++dt) o[dt] = (f32x4){0.f, 0.f, 0.f, 0.f};
; #pragma unroll
;             for (int t = 0; t < 9; ++t) {
;                 const int kt = ktb + t > 0 ? ktb + t : 0;
; #pragma unroll
;                 for (int dt = 0; dt < 4; ++dt) {
;                     const s16x4 vf = *(const LAS s16x4*)(F.lds + VOFF + (dt * 16 + fr) * VSTR + (kt * 16 - k_lo + fq * 4) * 2);
;                     o[dt] = __builtin_amdgcn_mfma_f32_16x16x16bf16_1k(vf, pf[t], o[dt], 0, 0, 0);
;                 }
;             }
;             bf16_t* op = F.OB + (size_t)qrow * D + h * 64 + fq * 4;
; #pragma unroll
;             for (int dt = 0; dt < 4; ++dt) { u32x2 w; w.x = cvt_pk_bf16(o[dt][0] * rden, o[dt][1] * rden); w.y = cvt_pk_bf16(o[dt][2] * rden, o[dt][3] * rden); *(u32x2*)(op + dt * 16) = w; }
	v_add_f32_e32 v19, v19, v30
	ds_bpermute_b32 v30, v68, v19
	s_sub_i32 s10, s10, s26
	v_add_u32_e32 v58, s10, v70
	s_waitcnt lgkmcnt(2)
	v_mfma_f32_16x16x16_bf16 v[34:37], v[34:35], v[26:27], 0
	s_waitcnt lgkmcnt(0)
	v_add_f32_e32 v19, v19, v30
	v_fmamk_f32 v30, v73, 0x3fb8aa3b, v136
	v_exp_f32_e32 v30, v30
	v_mfma_f32_16x16x16_bf16 v[38:41], v[38:39], v[26:27], 0
	s_lshl_b32 s10, s36, 5
	s_sub_i32 s10, s10, s26
	v_add_f32_e32 v19, v30, v19
	ds_read_b64 v[30:31], v54 offset:29952
	ds_read_b64 v[54:55], v54 offset:49152
	s_waitcnt lgkmcnt(1)
	v_mfma_f32_16x16x16_bf16 v[30:33], v[30:31], v[26:27], 0
	s_waitcnt lgkmcnt(0)
	v_mfma_f32_16x16x16_bf16 v[54:57], v[54:55], v[26:27], 0
	ds_read_b64 v[26:27], v58 offset:29952
	s_waitcnt lgkmcnt(0)
	v_mfma_f32_16x16x16_bf16 v[30:33], v[26:27], v[24:25], v[30:33]
	ds_read_b64 v[26:27], v58 offset:36352
	s_waitcnt lgkmcnt(0)
	v_mfma_f32_16x16x16_bf16 v[34:37], v[26:27], v[24:25], v[34:37]
	ds_read_b64 v[26:27], v58 offset:42752
	s_waitcnt lgkmcnt(0)
	v_mfma_f32_16x16x16_bf16 v[38:41], v[26:27], v[24:25], v[38:41]
	ds_read_b64 v[26:27], v58 offset:49152
	s_waitcnt lgkmcnt(0)
	v_mfma_f32_16x16x16_bf16 v[24:27], v[26:27], v[24:25], v[54:57]
	s_nop 2
	v_add_u32_e32 v56, s10, v70
	ds_read_b64 v[54:55], v56 offset:29952
	s_lshl_b32 s10, s35, 5
	s_waitcnt lgkmcnt(0)
	v_mfma_f32_16x16x16_bf16 v[30:33], v[54:55], v[28:29], v[30:33]
	ds_read_b64 v[54:55], v56 offset:36352
	s_sub_i32 s10, s10, s26
	s_waitcnt lgkmcnt(0)
	v_mfma_f32_16x16x16_bf16 v[34:37], v[54:55], v[28:29], v[34:37]
	ds_read_b64 v[54:55], v56 offset:42752
	s_waitcnt lgkmcnt(0)
	v_mfma_f32_16x16x16_bf16 v[38:41], v[54:55], v[28:29], v[38:41]
	ds_read_b64 v[54:55], v56 offset:49152
	s_waitcnt lgkmcnt(0)
	v_mfma_f32_16x16x16_bf16 v[24:27], v[54:55], v[28:29], v[24:27]
	v_add_u32_e32 v54, s10, v70
	ds_read_b64 v[28:29], v54 offset:29952
	s_lshl_b32 s10, s34, 5
	s_waitcnt lgkmcnt(0)
	v_mfma_f32_16x16x16_bf16 v[28:31], v[28:29], v[22:23], v[30:33]
	s_nop 2
	ds_read_b64 v[32:33], v54 offset:36352
	s_sub_i32 s10, s10, s26
	s_waitcnt lgkmcnt(0)
	v_mfma_f32_16x16x16_bf16 v[32:35], v[32:33], v[22:23], v[34:37]
	s_nop 2
	ds_read_b64 v[36:37], v54 offset:42752
	s_waitcnt lgkmcnt(0)
	v_mfma_f32_16x16x16_bf16 v[36:39], v[36:37], v[22:23], v[38:41]
	s_nop 2
	ds_read_b64 v[40:41], v54 offset:49152
	s_waitcnt lgkmcnt(0)
	v_mfma_f32_16x16x16_bf16 v[22:25], v[40:41], v[22:23], v[24:27]
	v_add_u32_e32 v40, s10, v70
	s_nop 1
	ds_read_b64 v[26:27], v40 offset:29952
	s_lshl_b32 s10, s31, 5
	s_waitcnt lgkmcnt(0)
	v_mfma_f32_16x16x16_bf16 v[26:29], v[26:27], v[20:21], v[28:31]
	s_nop 2
	ds_read_b64 v[30:31], v40 offset:36352
	s_sub_i32 s10, s10, s26
	s_waitcnt lgkmcnt(0)
	v_mfma_f32_16x16x16_bf16 v[30:33], v[30:31], v[20:21], v[32:35]
	s_nop 2
	ds_read_b64 v[34:35], v40 offset:42752
	s_waitcnt lgkmcnt(0)
	v_mfma_f32_16x16x16_bf16 v[34:37], v[34:35], v[20:21], v[36:39]
	s_nop 2
	ds_read_b64 v[38:39], v40 offset:49152
	s_waitcnt lgkmcnt(0)
	v_mfma_f32_16x16x16_bf16 v[20:23], v[38:39], v[20:21], v[22:25]
	v_add_u32_e32 v38, s10, v70
	s_nop 1
	ds_read_b64 v[24:25], v38 offset:29952
	s_lshl_b32 s10, s30, 5
	s_waitcnt lgkmcnt(0)
	v_mfma_f32_16x16x16_bf16 v[24:27], v[24:25], v[16:17], v[26:29]
	s_nop 2
	ds_read_b64 v[28:29], v38 offset:36352
	s_sub_i32 s10, s10, s26
	s_waitcnt lgkmcnt(0)
	v_mfma_f32_16x16x16_bf16 v[28:31], v[28:29], v[16:17], v[30:33]
	s_nop 2
	ds_read_b64 v[32:33], v38 offset:42752
	s_waitcnt lgkmcnt(0)
	v_mfma_f32_16x16x16_bf16 v[32:35], v[32:33], v[16:17], v[34:37]
	s_nop 2
	ds_read_b64 v[36:37], v38 offset:49152
	s_waitcnt lgkmcnt(0)
	v_mfma_f32_16x16x16_bf16 v[20:23], v[36:37], v[16:17], v[20:23]
	v_add_u32_e32 v36, s10, v70
	ds_read_b64 v[16:17], v36 offset:29952
	s_lshl_b32 s10, s29, 5
	s_waitcnt lgkmcnt(0)
	v_mfma_f32_16x16x16_bf16 v[24:27], v[16:17], v[14:15], v[24:27]
	ds_read_b64 v[16:17], v36 offset:36352
	s_sub_i32 s10, s10, s26
	s_waitcnt lgkmcnt(0)
	v_mfma_f32_16x16x16_bf16 v[28:31], v[16:17], v[14:15], v[28:31]
	ds_read_b64 v[16:17], v36 offset:42752
	s_waitcnt lgkmcnt(0)
	v_mfma_f32_16x16x16_bf16 v[32:35], v[16:17], v[14:15], v[32:35]
	ds_read_b64 v[16:17], v36 offset:49152
	v_add_u32_e32 v36, s10, v70
	s_waitcnt lgkmcnt(0)
	v_mfma_f32_16x16x16_bf16 v[14:17], v[16:17], v[14:15], v[20:23]
	s_nop 2
	ds_read_b64 v[20:21], v36 offset:29952
	s_waitcnt lgkmcnt(0)
	v_mfma_f32_16x16x16_bf16 v[20:23], v[20:21], v[12:13], v[24:27]
	s_nop 2
	ds_read_b64 v[24:25], v36 offset:36352
	s_waitcnt lgkmcnt(0)
	v_mfma_f32_16x16x16_bf16 v[24:27], v[24:25], v[12:13], v[28:31]
	s_nop 2
	ds_read_b64 v[28:29], v36 offset:42752
	s_waitcnt lgkmcnt(0)
	v_mfma_f32_16x16x16_bf16 v[28:31], v[28:29], v[12:13], v[32:35]
	s_nop 2
	ds_read_b64 v[32:33], v36 offset:49152
	s_waitcnt lgkmcnt(0)
	v_mfma_f32_16x16x16_bf16 v[12:15], v[32:33], v[12:13], v[14:17]
	v_lshl_add_u32 v32, s28, 1, v70
	s_nop 1
	ds_read_b64 v[16:17], v32 offset:29952
	s_waitcnt lgkmcnt(0)
	v_mfma_f32_16x16x16_bf16 v[20:23], v[16:17], v[10:11], v[20:23]
	ds_read_b64 v[16:17], v32 offset:36352
	s_waitcnt lgkmcnt(0)
	v_mfma_f32_16x16x16_bf16 v[24:27], v[16:17], v[10:11], v[24:27]
	ds_read_b64 v[16:17], v32 offset:42752
	s_waitcnt lgkmcnt(0)
	v_mfma_f32_16x16x16_bf16 v[28:31], v[16:17], v[10:11], v[28:31]
	ds_read_b64 v[16:17], v32 offset:49152
	s_waitcnt lgkmcnt(0)
	v_mfma_f32_16x16x16_bf16 v[10:13], v[16:17], v[10:11], v[12:15]
	s_nop 2
	v_div_scale_f32 v14, s[10:11], v19, v19, 1.0
	v_rcp_f32_e32 v15, v14
	s_nop 0
	v_fma_f32 v16, -v14, v15, 1.0
	v_fmac_f32_e32 v15, v16, v15
	v_div_scale_f32 v16, vcc, 1.0, v19, 1.0
	v_mul_f32_e32 v17, v16, v15
	v_fma_f32 v32, -v14, v17, v16
	v_fmac_f32_e32 v17, v32, v15
	v_fma_f32 v14, -v14, v17, v16
	v_div_fmas_f32 v14, v14, v15, v17
	v_div_fixup_f32 v32, v14, v19, 1.0
	v_ashrrev_i32_e32 v19, 31, v18
	v_lshlrev_b64 v[14:15], 12, v[18:19]
	v_lshl_add_u64 v[14:15], s[86:87], 0, v[14:15]
	v_mul_f32_e32 v16, v32, v20
	v_mul_f32_e32 v17, v32, v21
	v_lshl_add_u64 v[14:15], v[14:15], 0, s[82:83]
	v_cvt_pk_bf16_f32 v16, v16, v17
	v_mul_f32_e32 v17, v32, v22
	v_lshl_add_u64 v[14:15], v[14:15], 0, v[168:169]
	v_mul_f32_e32 v18, v32, v23
	v_cvt_pk_bf16_f32 v17, v17, v18
	global_store_dwordx2 v[14:15], v[16:17], off
	v_mul_f32_e32 v16, v32, v24
	v_mul_f32_e32 v17, v32, v25
	v_cvt_pk_bf16_f32 v16, v16, v17
	v_mul_f32_e32 v17, v32, v26
	v_mul_f32_e32 v18, v32, v27
	v_cvt_pk_bf16_f32 v17, v17, v18
	global_store_dwordx2 v[14:15], v[16:17], off offset:32
	v_mul_f32_e32 v16, v32, v28
	v_mul_f32_e32 v17, v32, v29
	v_cvt_pk_bf16_f32 v16, v16, v17
	v_mul_f32_e32 v17, v32, v30
	v_mul_f32_e32 v10, v32, v10
	v_mul_f32_e32 v11, v32, v11
	v_mul_f32_e32 v18, v32, v31
	v_cvt_pk_bf16_f32 v17, v17, v18
	global_store_dwordx2 v[14:15], v[16:17], off offset:64
	v_cvt_pk_bf16_f32 v10, v10, v11
	v_mul_f32_e32 v11, v32, v12
	s_and_b64 vcc, exec, s[12:13]
	v_mul_f32_e32 v12, v32, v13
	v_cvt_pk_bf16_f32 v11, v11, v12
	global_store_dwordx2 v[14:15], v[10:11], off offset:96
	s_cbranch_vccz .LBB0_1296
; #define LAS __attribute__((address_space(3)))
; __device__ __forceinline__ unsigned cvt_pk_bf16(float lo, float hi) { unsigned r; asm volatile("v_cvt_pk_bf16_f32 %0, %1, %2" : "=v"(r) : "v"(lo), "v"(hi)); return r; }
; __device__ __forceinline__ void phase_attn(Frame& F, const Params& p, int j) {
;     ...
;         for (int mt = 0; mt < 5; ++mt) {
;             if (mt >= nmt) break;
;             const int qt0 = q_lo + 16 * mt, q = qt0 + fr;
;             const int qrow = prow(b, q);
;             const bf16x8 qf0 = qfa[mt][0], qf1 = qfa[mt][1];
;             const int ktb = (qt0 >> 4) - 8;
;             f32x4 s[9];
; #pragma unroll
;             for (int t = 0; t < 9; ++t) {
;                 const int kt = ktb + t > 0 ? ktb + t : 0;
;                 const LAS unsigned char* kp = F.lds + (kt * 16 - k_lo + fr) * KSTR + fq * 16;
;                 const bf16x8 kf0 = *(const LAS bf16x8*)kp, kf1 = *(const LAS bf16x8*)(kp + 64);
;                 s[t] = (f32x4){0.f, 0.f, 0.f, 0.f};
;                 s[t] = __builtin_amdgcn_mfma_f32_16x16x32_bf16(kf0, qf0, s[t], 0, 0, 0);
;                 s[t] = __builtin_amdgcn_mfma_f32_16x16x32_bf16(kf1, qf1, s[t], 0, 0, 0);
;             }
;             float m = sink;
; #pragma unroll
;             for (int t = 0; t < 9; ++t)
; #pragma unroll
;                 for (int jj = 0; jj < 4; ++jj) { const int key = (ktb + t) * 16 + fq * 4 + jj, dd = q - key; const bool ok = key >= 0 && dd >= 0 && dd < 128;
;                     s[t][jj] = ok ? s[t][jj] : -1e30f; m = fmaxf(m, s[t][jj]); }
;             m = fmaxf(m, __shfl_xor(m, 16)); m = fmaxf(m, __shfl_xor(m, 32));
;             float l = 0.f; s16x4 pf[9];
; #pragma unroll
;             for (int t = 0; t < 9; ++t) {
;                 float pe[4];
; #pragma unroll
;                 for (int jj = 0; jj < 4; ++jj) { pe[jj] = __expf(s[t][jj] - m); l += pe[jj]; }
;                 u32x2 w; w.x = cvt_pk_bf16(pe[0], pe[1]); w.y = cvt_pk_bf16(pe[2], pe[3]);
;                 pf[t] = __builtin_bit_cast(s16x4, w);
;             }
	ds_read_b128 v[10:13], v72
	ds_read_b128 v[14:17], v72 offset:64
	v_subrev_u32_e32 v18, s27, v126
	v_mad_u32_u24 v34, v18, s80, v48
	ds_read_b128 v[18:21], v34 offset:2304
	ds_read_b128 v[22:25], v34 offset:2368
	s_waitcnt vmcnt(17) lgkmcnt(3)
	v_mfma_f32_16x16x32_bf16 v[10:13], v[10:13], v[6:9], 0
	s_waitcnt lgkmcnt(1)
	v_mfma_f32_16x16x32_bf16 v[18:21], v[18:21], v[6:9], 0
	s_waitcnt vmcnt(16)
	v_mfma_f32_16x16x32_bf16 v[14:17], v[14:17], v[2:5], v[10:13]
	s_nop 3
	ds_read_b128 v[10:13], v34 offset:4608
	s_waitcnt lgkmcnt(1)
	v_mfma_f32_16x16x32_bf16 v[18:21], v[22:25], v[2:5], v[18:21]
	ds_read_b128 v[22:25], v34 offset:4672
	ds_read_b128 v[26:29], v34 offset:6912
	ds_read_b128 v[30:33], v34 offset:6976
	s_waitcnt lgkmcnt(3)
	v_mfma_f32_16x16x32_bf16 v[10:13], v[10:13], v[6:9], 0
	s_waitcnt lgkmcnt(2)
	v_mfma_f32_16x16x32_bf16 v[36:39], v[22:25], v[2:5], v[10:13]
	ds_read_b128 v[22:25], v34 offset:9216
	ds_read_b128 v[54:57], v34 offset:9280
	v_max_f32_e32 v34, v73, v73
	s_waitcnt lgkmcnt(3)
	v_mfma_f32_16x16x32_bf16 v[10:13], v[26:29], v[6:9], 0
	v_max_f32_e32 v26, 0xf149f2ca, v34
	v_max3_f32 v26, v26, v14, v15
	v_max3_f32 v26, v26, v16, v17
	s_waitcnt lgkmcnt(1)
	v_mfma_f32_16x16x32_bf16 v[6:9], v[22:25], v[6:9], 0
	v_max3_f32 v26, v26, v18, v19
	v_max3_f32 v26, v26, v20, v21
	v_max3_f32 v26, v26, v36, v37
	v_mfma_f32_16x16x32_bf16 v[10:13], v[30:33], v[2:5], v[10:13]
	v_max3_f32 v22, v26, v38, v39
	s_waitcnt lgkmcnt(0)
	v_mfma_f32_16x16x32_bf16 v[2:5], v[54:57], v[2:5], v[6:9]
	s_nop 4
	v_max3_f32 v22, v22, v10, v11
	v_max3_f32 v22, v22, v12, v13
	s_nop 0
	v_cndmask_b32_e64 v2, v219, v2, s[2:3]
	v_cndmask_b32_e64 v3, v219, v3, s[4:5]
	v_max3_f32 v6, v22, v2, v3
	v_cndmask_b32_e64 v4, v219, v4, s[6:7]
	v_cndmask_b32_e64 v5, v219, v5, s[8:9]
	v_max3_f32 v6, v6, v4, v5
	ds_bpermute_b32 v7, v67, v6
	s_waitcnt lgkmcnt(0)
	v_max_f32_e32 v7, v7, v7
	v_max_f32_e32 v6, v6, v7
	ds_bpermute_b32 v7, v68, v6
	s_waitcnt lgkmcnt(0)
	v_max_f32_e32 v7, v7, v7
	v_max_f32_e32 v34, v6, v7
	v_mul_f32_e32 v136, 0xbfb8aa3b, v34
	v_sub_f32_e32 v6, 0xf149f2ca, v34
	v_mul_f32_e32 v6, 0x3fb8aa3b, v6
	v_exp_f32_e32 v35, v6
	v_fmamk_f32 v6, v14, 0x3fb8aa3b, v136
	v_exp_f32_e32 v82, v6
	v_fmamk_f32 v6, v15, 0x3fb8aa3b, v136
	v_exp_f32_e32 v83, v6
	v_fmamk_f32 v6, v16, 0x3fb8aa3b, v136
	v_exp_f32_e32 v84, v6
	v_fmamk_f32 v6, v17, 0x3fb8aa3b, v136
	v_exp_f32_e32 v85, v6
	v_fmamk_f32 v6, v18, 0x3fb8aa3b, v136
	v_exp_f32_e32 v86, v6
	v_fmamk_f32 v6, v19, 0x3fb8aa3b, v136
	v_exp_f32_e32 v87, v6
	v_fmamk_f32 v6, v20, 0x3fb8aa3b, v136
	v_exp_f32_e32 v88, v6
	v_fmamk_f32 v6, v21, 0x3fb8aa3b, v136
	v_exp_f32_e32 v89, v6
	v_fmamk_f32 v6, v36, 0x3fb8aa3b, v136
	v_exp_f32_e32 v90, v6
	v_fmamk_f32 v6, v37, 0x3fb8aa3b, v136
	v_exp_f32_e32 v91, v6
	v_fmamk_f32 v6, v38, 0x3fb8aa3b, v136
	v_exp_f32_e32 v92, v6
	v_fmamk_f32 v6, v39, 0x3fb8aa3b, v136
	v_exp_f32_e32 v93, v6
	v_fmamk_f32 v2, v2, 0x3fb8aa3b, v136
	v_fmamk_f32 v6, v10, 0x3fb8aa3b, v136
	v_exp_f32_e32 v98, v2
	v_exp_f32_e32 v94, v6
	v_fmamk_f32 v2, v3, 0x3fb8aa3b, v136
	v_fmamk_f32 v6, v11, 0x3fb8aa3b, v136
	v_exp_f32_e32 v99, v2
	v_exp_f32_e32 v95, v6
	v_fmamk_f32 v2, v4, 0x3fb8aa3b, v136
	v_fmamk_f32 v6, v12, 0x3fb8aa3b, v136
	v_exp_f32_e32 v100, v2
	v_exp_f32_e32 v96, v6
	v_fmamk_f32 v2, v5, 0x3fb8aa3b, v136
	v_fmamk_f32 v6, v13, 0x3fb8aa3b, v136
	v_exp_f32_e32 v101, v2
	v_add_u32_e32 v2, 0x7000, v70
	v_cvt_pk_bf16_f32 v24, v35, v35
	v_cvt_pk_bf16_f32 v25, v35, v35
	v_cvt_pk_bf16_f32 v26, v35, v35
	v_cvt_pk_bf16_f32 v27, v35, v35
	v_cvt_pk_bf16_f32 v28, v35, v35
	v_cvt_pk_bf16_f32 v29, v35, v35
	v_cvt_pk_bf16_f32 v40, v35, v35
	v_cvt_pk_bf16_f32 v41, v35, v35
	v_cvt_pk_bf16_f32 v30, v82, v83
	v_cvt_pk_bf16_f32 v31, v84, v85
	v_cvt_pk_bf16_f32 v32, v86, v87
	v_cvt_pk_bf16_f32 v33, v88, v89
	v_cvt_pk_bf16_f32 v22, v90, v91
	v_cvt_pk_bf16_f32 v23, v92, v93
	v_exp_f32_e32 v97, v6
	v_cvt_pk_bf16_f32 v20, v94, v95
	v_cvt_pk_bf16_f32 v21, v96, v97
	v_cvt_pk_bf16_f32 v18, v98, v99
	v_cvt_pk_bf16_f32 v19, v100, v101
	ds_read2_b64 v[14:17], v2 offset0:160 offset1:176
	v_add_u32_e32 v2, 0x8800, v70
	ds_read2_b64 v[10:13], v2 offset0:192 offset1:208
	v_add_u32_e32 v2, 0xa000, v70
	ds_read2_b64 v[6:9], v2 offset0:224 offset1:240
	v_add_u32_e32 v2, 0xc000, v70
	ds_read2_b64 v[2:5], v2 offset1:16
	s_waitcnt lgkmcnt(3)
	v_mfma_f32_16x16x16_bf16 v[36:39], v[14:15], v[24:25], 0
	s_waitcnt lgkmcnt(1)
	v_mfma_f32_16x16x16_bf16 v[58:61], v[6:7], v[24:25], 0
	v_mfma_f32_16x16x16_bf16 v[54:57], v[10:11], v[24:25], 0
	s_waitcnt lgkmcnt(0)
; #define LAS __attribute__((address_space(3)))
; __device__ __forceinline__ unsigned cvt_pk_bf16(float lo, float hi) { unsigned r; asm volatile("v_cvt_pk_bf16_f32 %0, %1, %2" : "=v"(r) : "v"(lo), "v"(hi)); return r; }
; __device__ __forceinline__ void phase_attn(Frame& F, const Params& p, int j) {
;     ...
;             l += __shfl_xor(l, 16); l += __shfl_xor(l, 32);
;             const float rden = 1.0f / (l + __expf(sink - m));
;             f32x4 o[4];
; #pragma unroll
;             for (int dt = 0; dt < 4; ++dt) o[dt] = (f32x4){0.f, 0.f, 0.f, 0.f};
; #pragma unroll
;             for (int t = 0; t < 9; ++t) {
;                 const int kt = ktb + t > 0 ? ktb + t : 0;
; #pragma unroll
;                 for (int dt = 0; dt < 4; ++dt) {
;                     const s16x4 vf = *(const LAS s16x4*)(F.lds + VOFF + (dt * 16 + fr) * VSTR + (kt * 16 - k_lo + fq * 4) * 2);
;                     o[dt] = __builtin_amdgcn_mfma_f32_16x16x16bf16_1k(vf, pf[t], o[dt], 0, 0, 0);
;                 }
;             }
;             bf16_t* op = F.OB + (size_t)qrow * D + h * 64 + fq * 4;
; #pragma unroll
;             for (int dt = 0; dt < 4; ++dt) { u32x2 w; w.x = cvt_pk_bf16(o[dt][0] * rden, o[dt][1] * rden); w.y = cvt_pk_bf16(o[dt][2] * rden, o[dt][3] * rden); *(u32x2*)(op + dt * 16) = w; }
	v_mfma_f32_16x16x16_bf16 v[62:65], v[2:3], v[24:25], 0
	v_mfma_f32_16x16x16_bf16 v[36:39], v[14:15], v[26:27], v[36:39]
	v_mfma_f32_16x16x16_bf16 v[58:61], v[6:7], v[26:27], v[58:61]
	v_mfma_f32_16x16x16_bf16 v[54:57], v[10:11], v[26:27], v[54:57]
	v_mfma_f32_16x16x16_bf16 v[24:27], v[2:3], v[26:27], v[62:65]
	v_mfma_f32_16x16x16_bf16 v[36:39], v[14:15], v[28:29], v[36:39]
	v_mfma_f32_16x16x16_bf16 v[58:61], v[6:7], v[28:29], v[58:61]
	v_mfma_f32_16x16x16_bf16 v[54:57], v[10:11], v[28:29], v[54:57]
	v_mfma_f32_16x16x16_bf16 v[24:27], v[2:3], v[28:29], v[24:27]
	v_add_f32_e32 v28, 0, v35
	v_add_f32_e32 v28, v35, v28
	v_add_f32_e32 v28, v35, v28
	v_mfma_f32_16x16x16_bf16 v[36:39], v[14:15], v[40:41], v[36:39]
	v_add_f32_e32 v28, v35, v28
	v_mfma_f32_16x16x16_bf16 v[58:61], v[6:7], v[40:41], v[58:61]
	v_mfma_f32_16x16x16_bf16 v[24:27], v[2:3], v[40:41], v[24:27]
	v_mfma_f32_16x16x16_bf16 v[36:39], v[14:15], v[30:31], v[36:39]
	v_add_f32_e32 v14, v35, v28
	v_add_f32_e32 v14, v35, v14
	v_add_f32_e32 v14, v35, v14
	v_mfma_f32_16x16x16_bf16 v[58:61], v[6:7], v[30:31], v[58:61]
	v_add_f32_e32 v6, v35, v14
	v_subrev_u32_e32 v15, s26, v70
	v_add_u32_e32 v7, 0x8800, v15
	v_mfma_f32_16x16x16_bf16 v[24:27], v[2:3], v[30:31], v[24:27]
	v_add_f32_e32 v2, v35, v6
	v_add_f32_e32 v2, v35, v2
	v_add_f32_e32 v2, v35, v2
	v_mfma_f32_16x16x16_bf16 v[54:57], v[10:11], v[40:41], v[54:57]
	v_add_f32_e32 v2, v35, v2
	v_add_f32_e32 v2, v35, v2
	v_add_f32_e32 v2, v35, v2
	v_mfma_f32_16x16x16_bf16 v[54:57], v[10:11], v[30:31], v[54:57]
	v_add_u32_e32 v10, 0x7000, v15
	v_add_f32_e32 v2, v35, v2
	ds_read2_b64 v[62:65], v10 offset0:164 offset1:168
	v_add_f32_e32 v2, v35, v2
	v_add_u32_e32 v3, 0xa000, v15
	v_add_f32_e32 v2, v82, v2
	ds_read2_b64 v[28:31], v3 offset0:228 offset1:232
	v_add_u32_e32 v3, 0xc000, v15
	v_add_f32_e32 v2, v83, v2
	ds_read2_b64 v[74:77], v7 offset0:196 offset1:200
	ds_read2_b64 v[78:81], v3 offset0:4 offset1:8
	v_add_f32_e32 v2, v84, v2
	v_add_f32_e32 v2, v85, v2
	v_add_f32_e32 v2, v86, v2
	v_add_f32_e32 v2, v87, v2
	v_add_f32_e32 v2, v88, v2
	v_add_f32_e32 v6, v89, v2
	ds_read_b64 v[2:3], v15 offset:30048
	s_waitcnt lgkmcnt(4)
	v_mfma_f32_16x16x16_bf16 v[36:39], v[62:63], v[32:33], v[36:39]
	v_add_f32_e32 v6, v90, v6
	v_add_f32_e32 v10, v91, v6
	ds_read_b64 v[6:7], v15 offset:36448
	s_waitcnt lgkmcnt(3)
	v_mfma_f32_16x16x16_bf16 v[54:57], v[74:75], v[32:33], v[54:57]
	v_mfma_f32_16x16x16_bf16 v[58:61], v[28:29], v[32:33], v[58:61]
	s_waitcnt lgkmcnt(2)
	v_mfma_f32_16x16x16_bf16 v[24:27], v[78:79], v[32:33], v[24:27]
	v_mfma_f32_16x16x16_bf16 v[36:39], v[64:65], v[22:23], v[36:39]
	v_mfma_f32_16x16x16_bf16 v[54:57], v[76:77], v[22:23], v[54:57]
	v_mfma_f32_16x16x16_bf16 v[28:31], v[30:31], v[22:23], v[58:61]
	v_mfma_f32_16x16x16_bf16 v[22:25], v[80:81], v[22:23], v[24:27]
	s_nop 3
	v_add_f32_e32 v26, v92, v10
	s_waitcnt lgkmcnt(1)
	v_mfma_f32_16x16x16_bf16 v[36:39], v[2:3], v[20:21], v[36:39]
	v_add_f32_e32 v2, v93, v26
	v_add_f32_e32 v2, v94, v2
	v_add_f32_e32 v2, v95, v2
	v_add_f32_e32 v2, v96, v2
	v_add_f32_e32 v2, v97, v2
	v_add_f32_e32 v2, v98, v2
	v_add_f32_e32 v2, v99, v2
	v_add_f32_e32 v2, v100, v2
	v_add_f32_e32 v2, v101, v2
	ds_bpermute_b32 v3, v67, v2
	ds_read_b64 v[10:11], v15 offset:42848
	ds_read_b64 v[14:15], v15 offset:49248
	s_waitcnt lgkmcnt(3)
	v_mfma_f32_16x16x16_bf16 v[54:57], v[6:7], v[20:21], v[54:57]
	v_fmamk_f32 v6, v73, 0x3fb8aa3b, v136
	s_waitcnt lgkmcnt(2)
	v_add_f32_e32 v2, v2, v3
	ds_bpermute_b32 v3, v68, v2
	v_exp_f32_e32 v6, v6
	s_waitcnt lgkmcnt(2)
	v_mfma_f32_16x16x16_bf16 v[26:29], v[10:11], v[20:21], v[28:31]
	s_waitcnt lgkmcnt(0)
	v_add_f32_e32 v2, v2, v3
	v_mfma_f32_16x16x16_bf16 v[20:23], v[14:15], v[20:21], v[22:25]
	s_nop 2
	v_add_f32_e32 v25, v6, v2
	v_mfma_f32_16x16x16_bf16 v[6:9], v[8:9], v[18:19], v[26:29]
	v_add_u32_e32 v24, s25, v69
	s_nop 1
	v_div_scale_f32 v26, s[10:11], v25, v25, 1.0
	v_rcp_f32_e32 v27, v26
	v_mfma_f32_16x16x16_bf16 v[14:17], v[16:17], v[18:19], v[36:39]
	v_mfma_f32_16x16x16_bf16 v[10:13], v[12:13], v[18:19], v[54:57]
	v_mfma_f32_16x16x16_bf16 v[2:5], v[4:5], v[18:19], v[20:23]
	v_fma_f32 v18, -v26, v27, 1.0
	v_fmac_f32_e32 v27, v18, v27
	v_div_scale_f32 v18, vcc, 1.0, v25, 1.0
	v_mul_f32_e32 v19, v18, v27
	v_fma_f32 v20, -v26, v19, v18
	v_fmac_f32_e32 v19, v20, v27
	v_fma_f32 v18, -v26, v19, v18
	v_div_fmas_f32 v18, v18, v27, v19
	v_div_fixup_f32 v20, v18, v25, 1.0
	v_ashrrev_i32_e32 v25, 31, v24
	v_lshlrev_b64 v[18:19], 12, v[24:25]
	v_lshl_add_u64 v[18:19], s[86:87], 0, v[18:19]
	v_lshl_add_u64 v[18:19], v[18:19], 0, s[82:83]
	v_mul_f32_e32 v14, v20, v14
	v_mul_f32_e32 v15, v20, v15
	v_lshl_add_u64 v[18:19], v[18:19], 0, v[168:169]
	v_cvt_pk_bf16_f32 v14, v14, v15
	v_mul_f32_e32 v15, v20, v16
	v_mul_f32_e32 v10, v20, v10
	v_mul_f32_e32 v11, v20, v11
	v_mul_f32_e32 v16, v20, v17
	v_cvt_pk_bf16_f32 v15, v15, v16
	global_store_dwordx2 v[18:19], v[14:15], off
	v_cvt_pk_bf16_f32 v10, v10, v11
	v_mul_f32_e32 v11, v20, v12
	v_mul_f32_e32 v6, v20, v6
	v_mul_f32_e32 v7, v20, v7
	v_mul_f32_e32 v12, v20, v13
	v_cvt_pk_bf16_f32 v11, v11, v12
	global_store_dwordx2 v[18:19], v[10:11], off offset:32
	v_cvt_pk_bf16_f32 v6, v6, v7
	v_mul_f32_e32 v7, v20, v8
	v_mul_f32_e32 v2, v20, v2
	v_mul_f32_e32 v3, v20, v3
	v_mul_f32_e32 v8, v20, v9
	v_cvt_pk_bf16_f32 v7, v7, v8
	global_store_dwordx2 v[18:19], v[6:7], off offset:64
	v_cvt_pk_bf16_f32 v2, v2, v3
	v_mul_f32_e32 v3, v20, v4
	v_mul_f32_e32 v4, v20, v5
	v_cvt_pk_bf16_f32 v3, v3, v4
	global_store_dwordx2 v[18:19], v[2:3], off offset:96
	s_branch .LBB0_1296
